# baseline (speedup 1.0000x reference)
; #define PG8_STAGE(bufoff, gbase, voff) do { _Pragma("unroll") for (int _i = 0; _i < 2; ++_i) \
;         __builtin_amdgcn_global_load_lds((const unsigned*)((const char*)(gbase) + (voff)[_i]), (PG8_LAS unsigned*)(lds + (bufoff) + ldsw + _i * 8192), 16, 0, 0); } while (0)
; #define PG8_LDA(dst, b, h) do { _Pragma("unroll") for (int m = 0; m < 4; ++m) _Pragma("unroll") for (int k = 0; k < 2; ++k) dst[m][k] = *(const PG8_LAS bf16x8*)(lds + PG8_SA(b, h) + aoff + m * 2048 + k * 1024); } while (0)
; #define PG8_LDB(dst, b, h) do { _Pragma("unroll") for (int n = 0; n < 2; ++n) _Pragma("unroll") for (int k = 0; k < 2; ++k) dst[n][k] = *(const PG8_LAS bf16x8*)(lds + PG8_SB(b, h) + boff + n * 2048 + k * 1024); } while (0)
; #define PG8_MMA(ai, bj, At, Bt) do { __builtin_amdgcn_s_setprio(1); _Pragma("unroll") for (int m = 0; m < 4; ++m) _Pragma("unroll") for (int n = 0; n < 2; ++n) _Pragma("unroll") for (int k = 0; k < 2; ++k) \
;         acc[ai][bj][m][n] = __builtin_amdgcn_mfma_f32_16x16x32_bf16(Bt[n][k], At[m][k], acc[ai][bj][m][n], 0, 0, 0); __builtin_amdgcn_s_setprio(0); } while (0)
; #define PG8_WAIT_V(n) asm volatile("s_waitcnt vmcnt(" #n ")" ::: "memory")
; #define PG8_WAIT_L(n) asm volatile("s_waitcnt lgkmcnt(" #n ")" ::: "memory")
; #define PG8_BAR __builtin_amdgcn_s_barrier()
; #define PG8_SCHED __builtin_amdgcn_sched_barrier(0)
; template <class Epi, class Sched, bool ALIGN_EPI = false, bool SP2 = false>
; __device__ __forceinline__ void gemm_phase(PG8_LAS unsigned char* lds, const Gemm g, const Sched& S, const Epi& E, const int wv) {
;     ...
;             const bool last = (t == nt - 2);
;             const char* a1 = cA + (size_t)(t + 1) * kstep;
;             const char* a2 = last ? nA : cA + (size_t)(t + 2) * kstep; const char* b2 = last ? nB : cB + (size_t)(t + 2) * kstep;
;             const char* a3 = a2 + kstep; const char* b3 = b2 + kstep;
;             if (last && has_next) S.a_ready(nxt);
;             if constexpr (SP2) {
;             PG8_LDB(B0, 0, 0); PG8_LDB(B1, 0, 1); PG8_SCHED; PG8_LDA(At, 0, 0); PG8_STAGE(PG8_SA(1, 1), a1 + hstep, voffA);
;             PG8_WAIT_V(8); PG8_WAIT_L(0); PG8_BAR; PG8_MMA(0, 0, At, B0); PG8_MMA(0, 1, At, B1); PG8_BAR; PG8_SCHED;
;             PG8_LDA(At, 0, 1); PG8_STAGE(PG8_SB(0, 0), b2, voffB); PG8_STAGE(PG8_SB(0, 1), b2 + hstep, voffB); PG8_STAGE(PG8_SA(0, 0), a2, voffA);
.LBB0_134:
	s_add_u32 s26, s24, 0xfffc0080
	s_addc_u32 s27, s25, -1
	s_add_i32 s51, 0, 0x10000
	s_cmp_eq_u32 s50, 12
	s_cselect_b32 s29, s17, s27
	s_cselect_b32 s28, s23, s26
	v_add_u32_e32 v0, s51, v183
	s_cselect_b32 s27, s15, s49
	s_cselect_b32 s26, s33, s48
	s_add_i32 s54, 0, 0x14000
	ds_read_b128 v[142:145], v0
	ds_read_b128 v[146:149], v0 offset:1024
	ds_read_b128 v[150:153], v0 offset:2048
	ds_read_b128 v[154:157], v0 offset:3072
	v_add_u32_e32 v0, s54, v183
	ds_read_b128 v[158:161], v0
	ds_read_b128 v[162:165], v0 offset:1024
	ds_read_b128 v[166:169], v0 offset:2048
	ds_read_b128 v[170:173], v0 offset:3072
	v_lshl_add_u64 v[208:209], s[24:25], 0, v[138:139]
	s_add_i32 m0, s39, 0xc000
	ds_read_b128 v[174:177], v186
	ds_read_b128 v[178:181], v186 offset:1024
	ds_read_b128 v[188:191], v186 offset:2048
	ds_read_b128 v[192:195], v186 offset:3072
	ds_read_b128 v[196:199], v186 offset:4096
	ds_read_b128 v[200:203], v186 offset:5120
	ds_read_b128 v[204:207], v186 offset:6144
	ds_read_b128 v[218:221], v186 offset:7168
	global_load_lds_dwordx4 v[208:209], off
	v_lshl_add_u64 v[208:209], s[24:25], 0, v[140:141]
	s_add_i32 m0, s39, 0xe000
	s_nop 0
	global_load_lds_dwordx4 v[208:209], off
	s_waitcnt vmcnt(8)
	s_waitcnt lgkmcnt(0)
	s_setprio 1
	s_waitcnt lgkmcnt(0)
	s_barrier
	v_mfma_f32_16x16x32_bf16 v[126:129], v[142:145], v[174:177], v[126:129]
	v_mfma_f32_16x16x32_bf16 v[122:125], v[150:153], v[174:177], v[122:125]
	v_mfma_f32_16x16x32_bf16 v[110:113], v[142:145], v[188:191], v[110:113]
	v_mfma_f32_16x16x32_bf16 v[106:109], v[150:153], v[188:191], v[106:109]
	v_mfma_f32_16x16x32_bf16 v[94:97], v[142:145], v[196:199], v[94:97]
	v_mfma_f32_16x16x32_bf16 v[90:93], v[150:153], v[196:199], v[90:93]
	v_mfma_f32_16x16x32_bf16 v[78:81], v[142:145], v[204:207], v[78:81]
	v_mfma_f32_16x16x32_bf16 v[74:77], v[150:153], v[204:207], v[74:77]
	v_mfma_f32_16x16x32_bf16 v[126:129], v[146:149], v[178:181], v[126:129]
	v_mfma_f32_16x16x32_bf16 v[122:125], v[154:157], v[178:181], v[122:125]
	v_mfma_f32_16x16x32_bf16 v[110:113], v[146:149], v[192:195], v[110:113]
	v_mfma_f32_16x16x32_bf16 v[106:109], v[154:157], v[192:195], v[106:109]
	v_mfma_f32_16x16x32_bf16 v[94:97], v[146:149], v[200:203], v[94:97]
	v_mfma_f32_16x16x32_bf16 v[90:93], v[154:157], v[200:203], v[90:93]
	v_mfma_f32_16x16x32_bf16 v[78:81], v[146:149], v[218:221], v[78:81]
	v_mfma_f32_16x16x32_bf16 v[74:77], v[154:157], v[218:221], v[74:77]
	s_setprio 0
	s_setprio 1
	v_mfma_f32_16x16x32_bf16 v[118:121], v[158:161], v[174:177], v[118:121]
	v_mfma_f32_16x16x32_bf16 v[114:117], v[166:169], v[174:177], v[114:117]
	v_mfma_f32_16x16x32_bf16 v[102:105], v[158:161], v[188:191], v[102:105]
	v_mfma_f32_16x16x32_bf16 v[98:101], v[166:169], v[188:191], v[98:101]
	v_mfma_f32_16x16x32_bf16 v[86:89], v[158:161], v[196:199], v[86:89]
	v_mfma_f32_16x16x32_bf16 v[82:85], v[166:169], v[196:199], v[82:85]
	v_mfma_f32_16x16x32_bf16 v[70:73], v[158:161], v[204:207], v[70:73]
	v_mfma_f32_16x16x32_bf16 v[66:69], v[166:169], v[204:207], v[66:69]
	v_mfma_f32_16x16x32_bf16 v[118:121], v[162:165], v[178:181], v[118:121]
	v_mfma_f32_16x16x32_bf16 v[114:117], v[170:173], v[178:181], v[114:117]
	v_mfma_f32_16x16x32_bf16 v[102:105], v[162:165], v[192:195], v[102:105]
	v_mfma_f32_16x16x32_bf16 v[98:101], v[170:173], v[192:195], v[98:101]
	v_mfma_f32_16x16x32_bf16 v[86:89], v[162:165], v[200:203], v[86:89]
	v_mfma_f32_16x16x32_bf16 v[82:85], v[170:173], v[200:203], v[82:85]
	v_mfma_f32_16x16x32_bf16 v[70:73], v[162:165], v[218:221], v[70:73]
	v_mfma_f32_16x16x32_bf16 v[66:69], v[170:173], v[218:221], v[66:69]
	s_barrier
	s_setprio 0
	s_add_i32 s51, s51, s35
	v_lshl_add_u64 v[208:209], s[26:27], 0, v[134:135]
	s_mov_b32 m0, s51
	ds_read_b128 v[174:177], v186 offset:16384
	ds_read_b128 v[178:181], v186 offset:17408
	ds_read_b128 v[188:191], v186 offset:18432
	ds_read_b128 v[192:195], v186 offset:19456
	ds_read_b128 v[196:199], v186 offset:20480
	ds_read_b128 v[200:203], v186 offset:21504
	ds_read_b128 v[204:207], v186 offset:22528
	ds_read_b128 v[218:221], v186 offset:23552
	global_load_lds_dwordx4 v[208:209], off
	s_add_i32 m0, s51, 0x2000
	s_add_u32 s52, s26, 0x40000
	v_lshl_add_u64 v[210:211], s[26:27], 0, v[130:131]
	s_addc_u32 s53, s27, 0
	s_add_i32 s51, s54, s35
	global_load_lds_dwordx4 v[210:211], off
	v_lshl_add_u64 v[212:213], s[52:53], 0, v[134:135]
	s_mov_b32 m0, s51
	v_lshl_add_u64 v[214:215], s[28:29], 0, v[132:133]
	global_load_lds_dwordx4 v[212:213], off
	v_lshl_add_u64 v[212:213], s[52:53], 0, v[130:131]
	s_add_i32 m0, s51, 0x2000
	s_nop 0
	global_load_lds_dwordx4 v[212:213], off
	v_lshl_add_u64 v[212:213], s[28:29], 0, v[136:137]
	s_mov_b32 m0, s39
	s_nop 0
	global_load_lds_dwordx4 v[212:213], off
	s_mov_b32 m0, s40
	s_nop 0
	global_load_lds_dwordx4 v[214:215], off
	s_waitcnt vmcnt(8)
	s_waitcnt lgkmcnt(0)
	s_setprio 1
	s_waitcnt lgkmcnt(0)
	s_barrier
; #define PG8_STAGE(bufoff, gbase, voff) do { _Pragma("unroll") for (int _i = 0; _i < 2; ++_i) \
;         __builtin_amdgcn_global_load_lds((const unsigned*)((const char*)(gbase) + (voff)[_i]), (PG8_LAS unsigned*)(lds + (bufoff) + ldsw + _i * 8192), 16, 0, 0); } while (0)
; #define PG8_LDA(dst, b, h) do { _Pragma("unroll") for (int m = 0; m < 4; ++m) _Pragma("unroll") for (int k = 0; k < 2; ++k) dst[m][k] = *(const PG8_LAS bf16x8*)(lds + PG8_SA(b, h) + aoff + m * 2048 + k * 1024); } while (0)
; #define PG8_LDB(dst, b, h) do { _Pragma("unroll") for (int n = 0; n < 2; ++n) _Pragma("unroll") for (int k = 0; k < 2; ++k) dst[n][k] = *(const PG8_LAS bf16x8*)(lds + PG8_SB(b, h) + boff + n * 2048 + k * 1024); } while (0)
; #define PG8_MMA(ai, bj, At, Bt) do { __builtin_amdgcn_s_setprio(1); _Pragma("unroll") for (int m = 0; m < 4; ++m) _Pragma("unroll") for (int n = 0; n < 2; ++n) _Pragma("unroll") for (int k = 0; k < 2; ++k) \
;         acc[ai][bj][m][n] = __builtin_amdgcn_mfma_f32_16x16x32_bf16(Bt[n][k], At[m][k], acc[ai][bj][m][n], 0, 0, 0); __builtin_amdgcn_s_setprio(0); } while (0)
; #define PG8_WAIT_V(n) asm volatile("s_waitcnt vmcnt(" #n ")" ::: "memory")
; #define PG8_WAIT_L(n) asm volatile("s_waitcnt lgkmcnt(" #n ")" ::: "memory")
; #define PG8_BAR __builtin_amdgcn_s_barrier()
; #define PG8_SCHED __builtin_amdgcn_sched_barrier(0)
; template <class Epi, class Sched, bool ALIGN_EPI = false, bool SP2 = false>
; __device__ __forceinline__ void gemm_phase(PG8_LAS unsigned char* lds, const Gemm g, const Sched& S, const Epi& E, const int wv) {
;     ...
;             PG8_WAIT_V(8); PG8_WAIT_L(0); PG8_BAR; PG8_MMA(1, 0, At, B0); PG8_MMA(1, 1, At, B1); PG8_BAR; PG8_SCHED;
;             PG8_LDB(B0, 1, 0); PG8_LDB(B1, 1, 1); PG8_SCHED; PG8_LDA(At, 1, 0); PG8_STAGE(PG8_SA(0, 1), a2 + hstep, voffA);
;             PG8_WAIT_V(8); PG8_WAIT_L(0); PG8_BAR; PG8_MMA(0, 0, At, B0); PG8_MMA(0, 1, At, B1); PG8_BAR; PG8_SCHED;
	v_mfma_f32_16x16x32_bf16 v[62:65], v[142:145], v[174:177], v[62:65]
	v_mfma_f32_16x16x32_bf16 v[58:61], v[150:153], v[174:177], v[58:61]
	v_mfma_f32_16x16x32_bf16 v[46:49], v[142:145], v[188:191], v[46:49]
	v_mfma_f32_16x16x32_bf16 v[42:45], v[150:153], v[188:191], v[42:45]
	v_mfma_f32_16x16x32_bf16 v[30:33], v[142:145], v[196:199], v[30:33]
	v_mfma_f32_16x16x32_bf16 v[26:29], v[150:153], v[196:199], v[26:29]
	v_mfma_f32_16x16x32_bf16 v[14:17], v[142:145], v[204:207], v[14:17]
	v_mfma_f32_16x16x32_bf16 v[10:13], v[150:153], v[204:207], v[10:13]
	v_mfma_f32_16x16x32_bf16 v[62:65], v[146:149], v[178:181], v[62:65]
	v_mfma_f32_16x16x32_bf16 v[58:61], v[154:157], v[178:181], v[58:61]
	v_mfma_f32_16x16x32_bf16 v[46:49], v[146:149], v[192:195], v[46:49]
	v_mfma_f32_16x16x32_bf16 v[42:45], v[154:157], v[192:195], v[42:45]
	v_mfma_f32_16x16x32_bf16 v[30:33], v[146:149], v[200:203], v[30:33]
	v_mfma_f32_16x16x32_bf16 v[26:29], v[154:157], v[200:203], v[26:29]
	v_mfma_f32_16x16x32_bf16 v[14:17], v[146:149], v[218:221], v[14:17]
	v_mfma_f32_16x16x32_bf16 v[10:13], v[154:157], v[218:221], v[10:13]
	s_setprio 0
	s_setprio 1
	v_mfma_f32_16x16x32_bf16 v[54:57], v[158:161], v[174:177], v[54:57]
	v_mfma_f32_16x16x32_bf16 v[50:53], v[166:169], v[174:177], v[50:53]
	v_mfma_f32_16x16x32_bf16 v[38:41], v[158:161], v[188:191], v[38:41]
	v_mfma_f32_16x16x32_bf16 v[34:37], v[166:169], v[188:191], v[34:37]
	v_mfma_f32_16x16x32_bf16 v[22:25], v[158:161], v[196:199], v[22:25]
	v_mfma_f32_16x16x32_bf16 v[18:21], v[166:169], v[196:199], v[18:21]
	v_mfma_f32_16x16x32_bf16 v[6:9], v[158:161], v[204:207], v[6:9]
	v_mfma_f32_16x16x32_bf16 v[2:5], v[166:169], v[204:207], v[2:5]
	v_mfma_f32_16x16x32_bf16 v[54:57], v[162:165], v[178:181], v[54:57]
	v_mfma_f32_16x16x32_bf16 v[50:53], v[170:173], v[178:181], v[50:53]
	v_mfma_f32_16x16x32_bf16 v[38:41], v[162:165], v[192:195], v[38:41]
	v_mfma_f32_16x16x32_bf16 v[34:37], v[170:173], v[192:195], v[34:37]
	v_mfma_f32_16x16x32_bf16 v[22:25], v[162:165], v[200:203], v[22:25]
	v_mfma_f32_16x16x32_bf16 v[18:21], v[170:173], v[200:203], v[18:21]
	v_mfma_f32_16x16x32_bf16 v[6:9], v[162:165], v[218:221], v[6:9]
	v_mfma_f32_16x16x32_bf16 v[2:5], v[170:173], v[218:221], v[2:5]
	s_barrier
	s_setprio 0
	s_add_i32 s51, 0, 0x18000
	v_add_u32_e32 v0, s51, v183
	s_add_i32 s52, 0, 0x1c000
	ds_read_b128 v[142:145], v0
	ds_read_b128 v[146:149], v0 offset:1024
	ds_read_b128 v[150:153], v0 offset:2048
	ds_read_b128 v[154:157], v0 offset:3072
	v_add_u32_e32 v0, s52, v183
	ds_read_b128 v[158:161], v0
	ds_read_b128 v[162:165], v0 offset:1024
	ds_read_b128 v[166:169], v0 offset:2048
	ds_read_b128 v[170:173], v0 offset:3072
	s_add_u32 s28, s28, 0x40000
	s_addc_u32 s29, s29, 0
	s_mov_b32 m0, s41
	v_lshl_add_u64 v[216:217], s[28:29], 0, v[136:137]
	ds_read_b128 v[174:177], v186 offset:32768
	ds_read_b128 v[178:181], v186 offset:33792
	ds_read_b128 v[188:191], v186 offset:34816
	ds_read_b128 v[192:195], v186 offset:35840
	ds_read_b128 v[196:199], v186 offset:36864
	ds_read_b128 v[200:203], v186 offset:37888
	ds_read_b128 v[204:207], v186 offset:38912
	ds_read_b128 v[218:221], v186 offset:39936
	global_load_lds_dwordx4 v[216:217], off
	v_lshl_add_u64 v[216:217], s[28:29], 0, v[132:133]
	s_mov_b32 m0, s42
	s_nop 0
	global_load_lds_dwordx4 v[216:217], off
	s_waitcnt vmcnt(8)
	s_waitcnt lgkmcnt(0)
	s_setprio 1
	s_waitcnt lgkmcnt(0)
	s_barrier
	v_mfma_f32_16x16x32_bf16 v[126:129], v[142:145], v[174:177], v[126:129]
	v_mfma_f32_16x16x32_bf16 v[122:125], v[150:153], v[174:177], v[122:125]
	v_mfma_f32_16x16x32_bf16 v[110:113], v[142:145], v[188:191], v[110:113]
	v_mfma_f32_16x16x32_bf16 v[106:109], v[150:153], v[188:191], v[106:109]
	v_mfma_f32_16x16x32_bf16 v[94:97], v[142:145], v[196:199], v[94:97]
	v_mfma_f32_16x16x32_bf16 v[90:93], v[150:153], v[196:199], v[90:93]
	v_mfma_f32_16x16x32_bf16 v[78:81], v[142:145], v[204:207], v[78:81]
	v_mfma_f32_16x16x32_bf16 v[74:77], v[150:153], v[204:207], v[74:77]
	v_mfma_f32_16x16x32_bf16 v[126:129], v[146:149], v[178:181], v[126:129]
	v_mfma_f32_16x16x32_bf16 v[122:125], v[154:157], v[178:181], v[122:125]
	v_mfma_f32_16x16x32_bf16 v[110:113], v[146:149], v[192:195], v[110:113]
	v_mfma_f32_16x16x32_bf16 v[106:109], v[154:157], v[192:195], v[106:109]
	v_mfma_f32_16x16x32_bf16 v[94:97], v[146:149], v[200:203], v[94:97]
	v_mfma_f32_16x16x32_bf16 v[90:93], v[154:157], v[200:203], v[90:93]
	v_mfma_f32_16x16x32_bf16 v[78:81], v[146:149], v[218:221], v[78:81]
	v_mfma_f32_16x16x32_bf16 v[74:77], v[154:157], v[218:221], v[74:77]
	s_setprio 0
	s_setprio 1
	v_mfma_f32_16x16x32_bf16 v[118:121], v[158:161], v[174:177], v[118:121]
	v_mfma_f32_16x16x32_bf16 v[114:117], v[166:169], v[174:177], v[114:117]
	v_mfma_f32_16x16x32_bf16 v[102:105], v[158:161], v[188:191], v[102:105]
	v_mfma_f32_16x16x32_bf16 v[98:101], v[166:169], v[188:191], v[98:101]
	v_mfma_f32_16x16x32_bf16 v[86:89], v[158:161], v[196:199], v[86:89]
	v_mfma_f32_16x16x32_bf16 v[82:85], v[166:169], v[196:199], v[82:85]
	v_mfma_f32_16x16x32_bf16 v[70:73], v[158:161], v[204:207], v[70:73]
	v_mfma_f32_16x16x32_bf16 v[66:69], v[166:169], v[204:207], v[66:69]
	v_mfma_f32_16x16x32_bf16 v[118:121], v[162:165], v[178:181], v[118:121]
	v_mfma_f32_16x16x32_bf16 v[114:117], v[170:173], v[178:181], v[114:117]
	v_mfma_f32_16x16x32_bf16 v[102:105], v[162:165], v[192:195], v[102:105]
	v_mfma_f32_16x16x32_bf16 v[98:101], v[170:173], v[192:195], v[98:101]
	v_mfma_f32_16x16x32_bf16 v[86:89], v[162:165], v[200:203], v[86:89]
	v_mfma_f32_16x16x32_bf16 v[82:85], v[170:173], v[200:203], v[82:85]
	v_mfma_f32_16x16x32_bf16 v[70:73], v[162:165], v[218:221], v[70:73]
	v_mfma_f32_16x16x32_bf16 v[66:69], v[170:173], v[218:221], v[66:69]
	s_barrier
; #define PG8_STAGE(bufoff, gbase, voff) do { _Pragma("unroll") for (int _i = 0; _i < 2; ++_i) \
;         __builtin_amdgcn_global_load_lds((const unsigned*)((const char*)(gbase) + (voff)[_i]), (PG8_LAS unsigned*)(lds + (bufoff) + ldsw + _i * 8192), 16, 0, 0); } while (0)
; #define PG8_LDA(dst, b, h) do { _Pragma("unroll") for (int m = 0; m < 4; ++m) _Pragma("unroll") for (int k = 0; k < 2; ++k) dst[m][k] = *(const PG8_LAS bf16x8*)(lds + PG8_SA(b, h) + aoff + m * 2048 + k * 1024); } while (0)
; #define PG8_MMA(ai, bj, At, Bt) do { __builtin_amdgcn_s_setprio(1); _Pragma("unroll") for (int m = 0; m < 4; ++m) _Pragma("unroll") for (int n = 0; n < 2; ++n) _Pragma("unroll") for (int k = 0; k < 2; ++k) \
;         acc[ai][bj][m][n] = __builtin_amdgcn_mfma_f32_16x16x32_bf16(Bt[n][k], At[m][k], acc[ai][bj][m][n], 0, 0, 0); __builtin_amdgcn_s_setprio(0); } while (0)
; #define PG8_WAIT_V(n) asm volatile("s_waitcnt vmcnt(" #n ")" ::: "memory")
; #define PG8_WAIT_L(n) asm volatile("s_waitcnt lgkmcnt(" #n ")" ::: "memory")
; #define PG8_BAR __builtin_amdgcn_s_barrier()
; #define PG8_SCHED __builtin_amdgcn_sched_barrier(0)
; template <class Epi, class Sched, bool ALIGN_EPI = false, bool SP2 = false>
; __device__ __forceinline__ void gemm_phase(PG8_LAS unsigned char* lds, const Gemm g, const Sched& S, const Epi& E, const int wv) {
;     ...
;             PG8_LDA(At, 1, 1); PG8_STAGE(PG8_SB(1, 0), b3, voffB); PG8_STAGE(PG8_SB(1, 1), b3 + hstep, voffB); PG8_STAGE(PG8_SA(1, 0), a3, voffA);
;             PG8_WAIT_V(8); PG8_WAIT_L(0); PG8_BAR; PG8_MMA(1, 0, At, B0); PG8_MMA(1, 1, At, B1); PG8_BAR; PG8_SCHED;
;     ...
;         if constexpr (ALIGN_EPI) { if (wr == 0) PG8_BAR; }
	s_setprio 0
	s_add_i32 s28, s51, s35
	v_lshl_add_u64 v[208:209], v[208:209], 0, s[2:3]
	s_mov_b32 m0, s28
	ds_read_b128 v[174:177], v186 offset:49152
	ds_read_b128 v[178:181], v186 offset:50176
	ds_read_b128 v[188:191], v186 offset:51200
	ds_read_b128 v[192:195], v186 offset:52224
	ds_read_b128 v[196:199], v186 offset:53248
	ds_read_b128 v[200:203], v186 offset:54272
	ds_read_b128 v[204:207], v186 offset:55296
	ds_read_b128 v[218:221], v186 offset:56320
	global_load_lds_dwordx4 v[208:209], off
	s_add_i32 m0, s28, 0x2000
	s_add_u32 s26, s26, 0x40080
	v_lshl_add_u64 v[208:209], v[210:211], 0, s[2:3]
	s_addc_u32 s27, s27, 0
	s_add_i32 s28, s52, s35
	global_load_lds_dwordx4 v[208:209], off
	v_lshl_add_u64 v[208:209], s[26:27], 0, v[134:135]
	s_mov_b32 m0, s28
	s_nop 0
	global_load_lds_dwordx4 v[208:209], off
	v_lshl_add_u64 v[208:209], s[26:27], 0, v[130:131]
	s_add_i32 m0, s28, 0x2000
	s_nop 0
	global_load_lds_dwordx4 v[208:209], off
	v_lshl_add_u64 v[208:209], v[212:213], 0, s[2:3]
	s_mov_b32 m0, s44
	s_nop 0
	global_load_lds_dwordx4 v[208:209], off
	v_lshl_add_u64 v[208:209], v[214:215], 0, s[2:3]
	s_mov_b32 m0, s45
	s_nop 0
	global_load_lds_dwordx4 v[208:209], off
	s_waitcnt vmcnt(8)
	s_waitcnt lgkmcnt(0)
	s_setprio 1
	s_waitcnt lgkmcnt(0)
	s_barrier
	v_mfma_f32_16x16x32_bf16 v[62:65], v[142:145], v[174:177], v[62:65]
	v_mfma_f32_16x16x32_bf16 v[58:61], v[150:153], v[174:177], v[58:61]
	v_mfma_f32_16x16x32_bf16 v[46:49], v[142:145], v[188:191], v[46:49]
	v_mfma_f32_16x16x32_bf16 v[42:45], v[150:153], v[188:191], v[42:45]
	v_mfma_f32_16x16x32_bf16 v[30:33], v[142:145], v[196:199], v[30:33]
	v_mfma_f32_16x16x32_bf16 v[26:29], v[150:153], v[196:199], v[26:29]
	v_mfma_f32_16x16x32_bf16 v[14:17], v[142:145], v[204:207], v[14:17]
	v_mfma_f32_16x16x32_bf16 v[10:13], v[150:153], v[204:207], v[10:13]
	v_mfma_f32_16x16x32_bf16 v[62:65], v[146:149], v[178:181], v[62:65]
	v_mfma_f32_16x16x32_bf16 v[58:61], v[154:157], v[178:181], v[58:61]
	v_mfma_f32_16x16x32_bf16 v[46:49], v[146:149], v[192:195], v[46:49]
	v_mfma_f32_16x16x32_bf16 v[42:45], v[154:157], v[192:195], v[42:45]
	v_mfma_f32_16x16x32_bf16 v[30:33], v[146:149], v[200:203], v[30:33]
	v_mfma_f32_16x16x32_bf16 v[26:29], v[154:157], v[200:203], v[26:29]
	v_mfma_f32_16x16x32_bf16 v[14:17], v[146:149], v[218:221], v[14:17]
	v_mfma_f32_16x16x32_bf16 v[10:13], v[154:157], v[218:221], v[10:13]
	s_setprio 0
	s_setprio 1
	v_mfma_f32_16x16x32_bf16 v[54:57], v[158:161], v[174:177], v[54:57]
	v_mfma_f32_16x16x32_bf16 v[50:53], v[166:169], v[174:177], v[50:53]
	v_mfma_f32_16x16x32_bf16 v[38:41], v[158:161], v[188:191], v[38:41]
	v_mfma_f32_16x16x32_bf16 v[34:37], v[166:169], v[188:191], v[34:37]
	v_mfma_f32_16x16x32_bf16 v[22:25], v[158:161], v[196:199], v[22:25]
	v_mfma_f32_16x16x32_bf16 v[18:21], v[166:169], v[196:199], v[18:21]
	v_mfma_f32_16x16x32_bf16 v[6:9], v[158:161], v[204:207], v[6:9]
	v_mfma_f32_16x16x32_bf16 v[2:5], v[166:169], v[204:207], v[2:5]
	v_mfma_f32_16x16x32_bf16 v[54:57], v[162:165], v[178:181], v[54:57]
	v_mfma_f32_16x16x32_bf16 v[50:53], v[170:173], v[178:181], v[50:53]
	v_mfma_f32_16x16x32_bf16 v[38:41], v[162:165], v[192:195], v[38:41]
	v_mfma_f32_16x16x32_bf16 v[34:37], v[170:173], v[192:195], v[34:37]
	v_mfma_f32_16x16x32_bf16 v[22:25], v[162:165], v[200:203], v[22:25]
	v_mfma_f32_16x16x32_bf16 v[18:21], v[170:173], v[200:203], v[18:21]
	v_mfma_f32_16x16x32_bf16 v[6:9], v[162:165], v[218:221], v[6:9]
	v_mfma_f32_16x16x32_bf16 v[2:5], v[170:173], v[218:221], v[2:5]
	s_barrier
	s_setprio 0
	s_add_i32 s50, s50, 2
	s_add_u32 s24, s24, 0x100
	s_addc_u32 s25, s25, 0
	s_add_u32 s48, s48, 0x100
	s_addc_u32 s49, s49, 0
	s_cmp_gt_u32 s50, 13
	s_cbranch_scc0 .LBB0_134
	s_and_b64 vcc, exec, s[10:11]
	s_cbranch_vccz .LBB0_137
	s_barrier

; #define PG8_STAGE(bufoff, gbase, voff) do { _Pragma("unroll") for (int _i = 0; _i < 2; ++_i) \
;         __builtin_amdgcn_global_load_lds((const unsigned*)((const char*)(gbase) + (voff)[_i]), (PG8_LAS unsigned*)(lds + (bufoff) + ldsw + _i * 8192), 16, 0, 0); } while (0)
; #define PG8_LDA(dst, b, h) do { _Pragma("unroll") for (int m = 0; m < 4; ++m) _Pragma("unroll") for (int k = 0; k < 2; ++k) dst[m][k] = *(const PG8_LAS bf16x8*)(lds + PG8_SA(b, h) + aoff + m * 2048 + k * 1024); } while (0)
; #define PG8_LDB(dst, b, h) do { _Pragma("unroll") for (int n = 0; n < 2; ++n) _Pragma("unroll") for (int k = 0; k < 2; ++k) dst[n][k] = *(const PG8_LAS bf16x8*)(lds + PG8_SB(b, h) + boff + n * 2048 + k * 1024); } while (0)
; #define PG8_MMA(ai, bj, At, Bt) do { __builtin_amdgcn_s_setprio(1); _Pragma("unroll") for (int m = 0; m < 4; ++m) _Pragma("unroll") for (int n = 0; n < 2; ++n) _Pragma("unroll") for (int k = 0; k < 2; ++k) \
;         acc[ai][bj][m][n] = __builtin_amdgcn_mfma_f32_16x16x32_bf16(Bt[n][k], At[m][k], acc[ai][bj][m][n], 0, 0, 0); __builtin_amdgcn_s_setprio(0); } while (0)
; #define PG8_WAIT_V(n) asm volatile("s_waitcnt vmcnt(" #n ")" ::: "memory")
; #define PG8_WAIT_L(n) asm volatile("s_waitcnt lgkmcnt(" #n ")" ::: "memory")
; #define PG8_BAR __builtin_amdgcn_s_barrier()
; #define PG8_SCHED __builtin_amdgcn_sched_barrier(0)
; template <class Epi, class Sched, bool ALIGN_EPI = false, bool SP2 = false>
; __device__ __forceinline__ void gemm_phase(PG8_LAS unsigned char* lds, const Gemm g, const Sched& S, const Epi& E, const int wv) {
;     ...
;             const bool last = (t == nt - 2);
;             const char* a1 = cA + (size_t)(t + 1) * kstep;
;             const char* a2 = last ? nA : cA + (size_t)(t + 2) * kstep; const char* b2 = last ? nB : cB + (size_t)(t + 2) * kstep;
;             const char* a3 = a2 + kstep; const char* b3 = b2 + kstep;
;             if (last && has_next) S.a_ready(nxt);
;             if constexpr (SP2) {
;             PG8_LDB(B0, 0, 0); PG8_LDB(B1, 0, 1); PG8_SCHED; PG8_LDA(At, 0, 0); PG8_STAGE(PG8_SA(1, 1), a1 + hstep, voffA);
;             PG8_WAIT_V(8); PG8_WAIT_L(0); PG8_BAR; PG8_MMA(0, 0, At, B0); PG8_MMA(0, 1, At, B1); PG8_BAR; PG8_SCHED;
;             PG8_LDA(At, 0, 1); PG8_STAGE(PG8_SB(0, 0), b2, voffB); PG8_STAGE(PG8_SB(0, 1), b2 + hstep, voffB); PG8_STAGE(PG8_SA(0, 0), a2, voffA);
.LBB0_156:
	s_add_u32 s20, s18, 0xfffc0080
	s_addc_u32 s21, s19, -1
	s_add_i32 s45, 0, 0x10000
	s_cmp_eq_u32 s44, 12
	s_cselect_b32 s23, s11, s21
	s_cselect_b32 s22, s40, s20
	v_add_u32_e32 v152, s45, v155
	s_cselect_b32 s21, s9, s43
	s_cselect_b32 s20, s41, s42
	s_add_i32 s48, 0, 0x14000
	ds_read_b128 v[140:143], v152
	ds_read_b128 v[144:147], v152 offset:1024
	ds_read_b128 v[148:151], v152 offset:2048
	ds_read_b128 v[158:161], v152 offset:3072
	v_add_u32_e32 v152, s48, v155
	ds_read_b128 v[162:165], v152
	ds_read_b128 v[166:169], v152 offset:1024
	ds_read_b128 v[170:173], v152 offset:2048
	ds_read_b128 v[174:177], v152 offset:3072
	v_lshl_add_u64 v[152:153], s[18:19], 0, v[136:137]
	s_add_i32 m0, s17, 0xc000
	ds_read_b128 v[178:181], v157
	ds_read_b128 v[182:185], v157 offset:1024
	ds_read_b128 v[186:189], v157 offset:2048
	ds_read_b128 v[190:193], v157 offset:3072
	ds_read_b128 v[194:197], v157 offset:4096
	ds_read_b128 v[198:201], v157 offset:5120
	ds_read_b128 v[202:205], v157 offset:6144
	ds_read_b128 v[206:209], v157 offset:7168
	global_load_lds_dwordx4 v[152:153], off
	v_lshl_add_u64 v[152:153], s[18:19], 0, v[138:139]
	s_add_i32 m0, s17, 0xe000
	s_nop 0
	global_load_lds_dwordx4 v[152:153], off
	s_waitcnt vmcnt(8)
	s_waitcnt lgkmcnt(0)
	s_setprio 1
	s_waitcnt lgkmcnt(0)
	s_barrier
	v_mfma_f32_16x16x32_bf16 v[126:129], v[140:143], v[178:181], v[126:129]
	v_mfma_f32_16x16x32_bf16 v[122:125], v[148:151], v[178:181], v[122:125]
	v_mfma_f32_16x16x32_bf16 v[118:121], v[140:143], v[186:189], v[118:121]
	v_mfma_f32_16x16x32_bf16 v[114:117], v[148:151], v[186:189], v[114:117]
	v_mfma_f32_16x16x32_bf16 v[98:101], v[140:143], v[194:197], v[98:101]
	v_mfma_f32_16x16x32_bf16 v[90:93], v[148:151], v[194:197], v[90:93]
	v_mfma_f32_16x16x32_bf16 v[78:81], v[140:143], v[202:205], v[78:81]
	v_mfma_f32_16x16x32_bf16 v[74:77], v[148:151], v[202:205], v[74:77]
	v_mfma_f32_16x16x32_bf16 v[126:129], v[144:147], v[182:185], v[126:129]
	v_mfma_f32_16x16x32_bf16 v[122:125], v[158:161], v[182:185], v[122:125]
	v_mfma_f32_16x16x32_bf16 v[118:121], v[144:147], v[190:193], v[118:121]
	v_mfma_f32_16x16x32_bf16 v[114:117], v[158:161], v[190:193], v[114:117]
	v_mfma_f32_16x16x32_bf16 v[98:101], v[144:147], v[198:201], v[98:101]
	v_mfma_f32_16x16x32_bf16 v[90:93], v[158:161], v[198:201], v[90:93]
	v_mfma_f32_16x16x32_bf16 v[78:81], v[144:147], v[206:209], v[78:81]
	v_mfma_f32_16x16x32_bf16 v[74:77], v[158:161], v[206:209], v[74:77]
	s_setprio 0
	s_setprio 1
	v_mfma_f32_16x16x32_bf16 v[110:113], v[162:165], v[178:181], v[110:113]
	v_mfma_f32_16x16x32_bf16 v[106:109], v[170:173], v[178:181], v[106:109]
	v_mfma_f32_16x16x32_bf16 v[102:105], v[162:165], v[186:189], v[102:105]
	v_mfma_f32_16x16x32_bf16 v[94:97], v[170:173], v[186:189], v[94:97]
	v_mfma_f32_16x16x32_bf16 v[86:89], v[162:165], v[194:197], v[86:89]
	v_mfma_f32_16x16x32_bf16 v[82:85], v[170:173], v[194:197], v[82:85]
	v_mfma_f32_16x16x32_bf16 v[70:73], v[162:165], v[202:205], v[70:73]
	v_mfma_f32_16x16x32_bf16 v[66:69], v[170:173], v[202:205], v[66:69]
	v_mfma_f32_16x16x32_bf16 v[110:113], v[166:169], v[182:185], v[110:113]
	v_mfma_f32_16x16x32_bf16 v[106:109], v[174:177], v[182:185], v[106:109]
	v_mfma_f32_16x16x32_bf16 v[102:105], v[166:169], v[190:193], v[102:105]
	v_mfma_f32_16x16x32_bf16 v[94:97], v[174:177], v[190:193], v[94:97]
	v_mfma_f32_16x16x32_bf16 v[86:89], v[166:169], v[198:201], v[86:89]
	v_mfma_f32_16x16x32_bf16 v[82:85], v[174:177], v[198:201], v[82:85]
	v_mfma_f32_16x16x32_bf16 v[70:73], v[166:169], v[206:209], v[70:73]
	v_mfma_f32_16x16x32_bf16 v[66:69], v[174:177], v[206:209], v[66:69]
	s_barrier
	s_setprio 0
	s_add_i32 s45, s45, s24
	v_lshl_add_u64 v[152:153], s[20:21], 0, v[0:1]
	s_mov_b32 m0, s45
	ds_read_b128 v[178:181], v157 offset:16384
	ds_read_b128 v[182:185], v157 offset:17408
	ds_read_b128 v[186:189], v157 offset:18432
	ds_read_b128 v[190:193], v157 offset:19456
	ds_read_b128 v[194:197], v157 offset:20480
	ds_read_b128 v[198:201], v157 offset:21504
	ds_read_b128 v[202:205], v157 offset:22528
	ds_read_b128 v[206:209], v157 offset:23552
	global_load_lds_dwordx4 v[152:153], off
	s_add_i32 m0, s45, 0x2000
	s_add_u32 s46, s20, 0x40000
	v_lshl_add_u64 v[210:211], s[20:21], 0, v[130:131]
	s_addc_u32 s47, s21, 0
	s_add_i32 s45, s48, s24
	global_load_lds_dwordx4 v[210:211], off
	v_lshl_add_u64 v[212:213], s[46:47], 0, v[0:1]
	s_mov_b32 m0, s45
	v_lshl_add_u64 v[214:215], s[22:23], 0, v[132:133]
	global_load_lds_dwordx4 v[212:213], off
	v_lshl_add_u64 v[212:213], s[46:47], 0, v[130:131]
	s_add_i32 m0, s45, 0x2000
	s_nop 0
	global_load_lds_dwordx4 v[212:213], off
	v_lshl_add_u64 v[212:213], s[22:23], 0, v[134:135]
	s_mov_b32 m0, s17
	s_nop 0
	global_load_lds_dwordx4 v[212:213], off
	s_mov_b32 m0, s26
	s_nop 0
	global_load_lds_dwordx4 v[214:215], off
	s_waitcnt vmcnt(8)
	s_waitcnt lgkmcnt(0)
	s_setprio 1
	s_waitcnt lgkmcnt(0)
	s_barrier
; #define PG8_STAGE(bufoff, gbase, voff) do { _Pragma("unroll") for (int _i = 0; _i < 2; ++_i) \
;         __builtin_amdgcn_global_load_lds((const unsigned*)((const char*)(gbase) + (voff)[_i]), (PG8_LAS unsigned*)(lds + (bufoff) + ldsw + _i * 8192), 16, 0, 0); } while (0)
; #define PG8_LDA(dst, b, h) do { _Pragma("unroll") for (int m = 0; m < 4; ++m) _Pragma("unroll") for (int k = 0; k < 2; ++k) dst[m][k] = *(const PG8_LAS bf16x8*)(lds + PG8_SA(b, h) + aoff + m * 2048 + k * 1024); } while (0)
; #define PG8_LDB(dst, b, h) do { _Pragma("unroll") for (int n = 0; n < 2; ++n) _Pragma("unroll") for (int k = 0; k < 2; ++k) dst[n][k] = *(const PG8_LAS bf16x8*)(lds + PG8_SB(b, h) + boff + n * 2048 + k * 1024); } while (0)
; #define PG8_MMA(ai, bj, At, Bt) do { __builtin_amdgcn_s_setprio(1); _Pragma("unroll") for (int m = 0; m < 4; ++m) _Pragma("unroll") for (int n = 0; n < 2; ++n) _Pragma("unroll") for (int k = 0; k < 2; ++k) \
;         acc[ai][bj][m][n] = __builtin_amdgcn_mfma_f32_16x16x32_bf16(Bt[n][k], At[m][k], acc[ai][bj][m][n], 0, 0, 0); __builtin_amdgcn_s_setprio(0); } while (0)
; #define PG8_WAIT_V(n) asm volatile("s_waitcnt vmcnt(" #n ")" ::: "memory")
; #define PG8_WAIT_L(n) asm volatile("s_waitcnt lgkmcnt(" #n ")" ::: "memory")
; #define PG8_BAR __builtin_amdgcn_s_barrier()
; #define PG8_SCHED __builtin_amdgcn_sched_barrier(0)
; template <class Epi, class Sched, bool ALIGN_EPI = false, bool SP2 = false>
; __device__ __forceinline__ void gemm_phase(PG8_LAS unsigned char* lds, const Gemm g, const Sched& S, const Epi& E, const int wv) {
;     ...
;             PG8_WAIT_V(8); PG8_WAIT_L(0); PG8_BAR; PG8_MMA(1, 0, At, B0); PG8_MMA(1, 1, At, B1); PG8_BAR; PG8_SCHED;
;             PG8_LDB(B0, 1, 0); PG8_LDB(B1, 1, 1); PG8_SCHED; PG8_LDA(At, 1, 0); PG8_STAGE(PG8_SA(0, 1), a2 + hstep, voffA);
;             PG8_WAIT_V(8); PG8_WAIT_L(0); PG8_BAR; PG8_MMA(0, 0, At, B0); PG8_MMA(0, 1, At, B1); PG8_BAR; PG8_SCHED;
	v_mfma_f32_16x16x32_bf16 v[62:65], v[140:143], v[178:181], v[62:65]
	v_mfma_f32_16x16x32_bf16 v[58:61], v[148:151], v[178:181], v[58:61]
	v_mfma_f32_16x16x32_bf16 v[46:49], v[140:143], v[186:189], v[46:49]
	v_mfma_f32_16x16x32_bf16 v[42:45], v[148:151], v[186:189], v[42:45]
	v_mfma_f32_16x16x32_bf16 v[30:33], v[140:143], v[194:197], v[30:33]
	v_mfma_f32_16x16x32_bf16 v[26:29], v[148:151], v[194:197], v[26:29]
	v_mfma_f32_16x16x32_bf16 v[14:17], v[140:143], v[202:205], v[14:17]
	v_mfma_f32_16x16x32_bf16 v[10:13], v[148:151], v[202:205], v[10:13]
	v_mfma_f32_16x16x32_bf16 v[62:65], v[144:147], v[182:185], v[62:65]
	v_mfma_f32_16x16x32_bf16 v[58:61], v[158:161], v[182:185], v[58:61]
	v_mfma_f32_16x16x32_bf16 v[46:49], v[144:147], v[190:193], v[46:49]
	v_mfma_f32_16x16x32_bf16 v[42:45], v[158:161], v[190:193], v[42:45]
	v_mfma_f32_16x16x32_bf16 v[30:33], v[144:147], v[198:201], v[30:33]
	v_mfma_f32_16x16x32_bf16 v[26:29], v[158:161], v[198:201], v[26:29]
	v_mfma_f32_16x16x32_bf16 v[14:17], v[144:147], v[206:209], v[14:17]
	v_mfma_f32_16x16x32_bf16 v[10:13], v[158:161], v[206:209], v[10:13]
	s_setprio 0
	s_setprio 1
	v_mfma_f32_16x16x32_bf16 v[54:57], v[162:165], v[178:181], v[54:57]
	v_mfma_f32_16x16x32_bf16 v[50:53], v[170:173], v[178:181], v[50:53]
	v_mfma_f32_16x16x32_bf16 v[38:41], v[162:165], v[186:189], v[38:41]
	v_mfma_f32_16x16x32_bf16 v[34:37], v[170:173], v[186:189], v[34:37]
	v_mfma_f32_16x16x32_bf16 v[22:25], v[162:165], v[194:197], v[22:25]
	v_mfma_f32_16x16x32_bf16 v[18:21], v[170:173], v[194:197], v[18:21]
	v_mfma_f32_16x16x32_bf16 v[6:9], v[162:165], v[202:205], v[6:9]
	v_mfma_f32_16x16x32_bf16 v[2:5], v[170:173], v[202:205], v[2:5]
	v_mfma_f32_16x16x32_bf16 v[54:57], v[166:169], v[182:185], v[54:57]
	v_mfma_f32_16x16x32_bf16 v[50:53], v[174:177], v[182:185], v[50:53]
	v_mfma_f32_16x16x32_bf16 v[38:41], v[166:169], v[190:193], v[38:41]
	v_mfma_f32_16x16x32_bf16 v[34:37], v[174:177], v[190:193], v[34:37]
	v_mfma_f32_16x16x32_bf16 v[22:25], v[166:169], v[198:201], v[22:25]
	v_mfma_f32_16x16x32_bf16 v[18:21], v[174:177], v[198:201], v[18:21]
	v_mfma_f32_16x16x32_bf16 v[6:9], v[166:169], v[206:209], v[6:9]
	v_mfma_f32_16x16x32_bf16 v[2:5], v[174:177], v[206:209], v[2:5]
	s_barrier
	s_setprio 0
	s_add_i32 s45, 0, 0x18000
	s_add_i32 s46, 0, 0x1c000
	v_add_u32_e32 v158, s45, v155
	v_add_u32_e32 v174, s46, v155
	ds_read_b128 v[140:143], v158
	ds_read_b128 v[144:147], v158 offset:1024
	ds_read_b128 v[148:151], v158 offset:2048
	ds_read_b128 v[158:161], v158 offset:3072
	ds_read_b128 v[162:165], v174
	ds_read_b128 v[166:169], v174 offset:1024
	ds_read_b128 v[170:173], v174 offset:2048
	ds_read_b128 v[174:177], v174 offset:3072
	s_add_u32 s22, s22, 0x40000
	s_addc_u32 s23, s23, 0
	s_mov_b32 m0, s27
	v_lshl_add_u64 v[216:217], s[22:23], 0, v[134:135]
	ds_read_b128 v[178:181], v157 offset:32768
	ds_read_b128 v[182:185], v157 offset:33792
	ds_read_b128 v[186:189], v157 offset:34816
	ds_read_b128 v[190:193], v157 offset:35840
	ds_read_b128 v[194:197], v157 offset:36864
	ds_read_b128 v[198:201], v157 offset:37888
	ds_read_b128 v[202:205], v157 offset:38912
	ds_read_b128 v[206:209], v157 offset:39936
	global_load_lds_dwordx4 v[216:217], off
	v_lshl_add_u64 v[216:217], s[22:23], 0, v[132:133]
	s_mov_b32 m0, s28
	s_nop 0
	global_load_lds_dwordx4 v[216:217], off
	s_waitcnt vmcnt(8)
	s_waitcnt lgkmcnt(0)
	s_setprio 1
	s_waitcnt lgkmcnt(0)
	s_barrier
	v_mfma_f32_16x16x32_bf16 v[126:129], v[140:143], v[178:181], v[126:129]
	v_mfma_f32_16x16x32_bf16 v[122:125], v[148:151], v[178:181], v[122:125]
	v_mfma_f32_16x16x32_bf16 v[118:121], v[140:143], v[186:189], v[118:121]
	v_mfma_f32_16x16x32_bf16 v[114:117], v[148:151], v[186:189], v[114:117]
	v_mfma_f32_16x16x32_bf16 v[98:101], v[140:143], v[194:197], v[98:101]
	v_mfma_f32_16x16x32_bf16 v[90:93], v[148:151], v[194:197], v[90:93]
	v_mfma_f32_16x16x32_bf16 v[78:81], v[140:143], v[202:205], v[78:81]
	v_mfma_f32_16x16x32_bf16 v[74:77], v[148:151], v[202:205], v[74:77]
	v_mfma_f32_16x16x32_bf16 v[126:129], v[144:147], v[182:185], v[126:129]
	v_mfma_f32_16x16x32_bf16 v[122:125], v[158:161], v[182:185], v[122:125]
	v_mfma_f32_16x16x32_bf16 v[118:121], v[144:147], v[190:193], v[118:121]
	v_mfma_f32_16x16x32_bf16 v[114:117], v[158:161], v[190:193], v[114:117]
	v_mfma_f32_16x16x32_bf16 v[98:101], v[144:147], v[198:201], v[98:101]
	v_mfma_f32_16x16x32_bf16 v[90:93], v[158:161], v[198:201], v[90:93]
	v_mfma_f32_16x16x32_bf16 v[78:81], v[144:147], v[206:209], v[78:81]
	v_mfma_f32_16x16x32_bf16 v[74:77], v[158:161], v[206:209], v[74:77]
	s_setprio 0
	s_setprio 1
	v_mfma_f32_16x16x32_bf16 v[110:113], v[162:165], v[178:181], v[110:113]
	v_mfma_f32_16x16x32_bf16 v[106:109], v[170:173], v[178:181], v[106:109]
	v_mfma_f32_16x16x32_bf16 v[102:105], v[162:165], v[186:189], v[102:105]
	v_mfma_f32_16x16x32_bf16 v[94:97], v[170:173], v[186:189], v[94:97]
	v_mfma_f32_16x16x32_bf16 v[86:89], v[162:165], v[194:197], v[86:89]
	v_mfma_f32_16x16x32_bf16 v[82:85], v[170:173], v[194:197], v[82:85]
	v_mfma_f32_16x16x32_bf16 v[70:73], v[162:165], v[202:205], v[70:73]
	v_mfma_f32_16x16x32_bf16 v[66:69], v[170:173], v[202:205], v[66:69]
	v_mfma_f32_16x16x32_bf16 v[110:113], v[166:169], v[182:185], v[110:113]
	v_mfma_f32_16x16x32_bf16 v[106:109], v[174:177], v[182:185], v[106:109]
	v_mfma_f32_16x16x32_bf16 v[102:105], v[166:169], v[190:193], v[102:105]
	v_mfma_f32_16x16x32_bf16 v[94:97], v[174:177], v[190:193], v[94:97]
	v_mfma_f32_16x16x32_bf16 v[86:89], v[166:169], v[198:201], v[86:89]
	v_mfma_f32_16x16x32_bf16 v[82:85], v[174:177], v[198:201], v[82:85]
	v_mfma_f32_16x16x32_bf16 v[70:73], v[166:169], v[206:209], v[70:73]
	v_mfma_f32_16x16x32_bf16 v[66:69], v[174:177], v[206:209], v[66:69]
	s_barrier
; #define PG8_STAGE(bufoff, gbase, voff) do { _Pragma("unroll") for (int _i = 0; _i < 2; ++_i) \
;         __builtin_amdgcn_global_load_lds((const unsigned*)((const char*)(gbase) + (voff)[_i]), (PG8_LAS unsigned*)(lds + (bufoff) + ldsw + _i * 8192), 16, 0, 0); } while (0)
; #define PG8_LDA(dst, b, h) do { _Pragma("unroll") for (int m = 0; m < 4; ++m) _Pragma("unroll") for (int k = 0; k < 2; ++k) dst[m][k] = *(const PG8_LAS bf16x8*)(lds + PG8_SA(b, h) + aoff + m * 2048 + k * 1024); } while (0)
; #define PG8_MMA(ai, bj, At, Bt) do { __builtin_amdgcn_s_setprio(1); _Pragma("unroll") for (int m = 0; m < 4; ++m) _Pragma("unroll") for (int n = 0; n < 2; ++n) _Pragma("unroll") for (int k = 0; k < 2; ++k) \
;         acc[ai][bj][m][n] = __builtin_amdgcn_mfma_f32_16x16x32_bf16(Bt[n][k], At[m][k], acc[ai][bj][m][n], 0, 0, 0); __builtin_amdgcn_s_setprio(0); } while (0)
; #define PG8_WAIT_V(n) asm volatile("s_waitcnt vmcnt(" #n ")" ::: "memory")
; #define PG8_WAIT_L(n) asm volatile("s_waitcnt lgkmcnt(" #n ")" ::: "memory")
; #define PG8_BAR __builtin_amdgcn_s_barrier()
; #define PG8_SCHED __builtin_amdgcn_sched_barrier(0)
; template <class Epi, class Sched, bool ALIGN_EPI = false, bool SP2 = false>
; __device__ __forceinline__ void gemm_phase(PG8_LAS unsigned char* lds, const Gemm g, const Sched& S, const Epi& E, const int wv) {
;     ...
;             PG8_LDA(At, 1, 1); PG8_STAGE(PG8_SB(1, 0), b3, voffB); PG8_STAGE(PG8_SB(1, 1), b3 + hstep, voffB); PG8_STAGE(PG8_SA(1, 0), a3, voffA);
;             PG8_WAIT_V(8); PG8_WAIT_L(0); PG8_BAR; PG8_MMA(1, 0, At, B0); PG8_MMA(1, 1, At, B1); PG8_BAR; PG8_SCHED;
;     ...
;         if constexpr (ALIGN_EPI) { if (wr == 0) PG8_BAR; }
	s_setprio 0
	s_add_i32 s22, s45, s24
	v_lshl_add_u64 v[152:153], v[152:153], 0, s[2:3]
	s_mov_b32 m0, s22
	ds_read_b128 v[178:181], v157 offset:49152
	ds_read_b128 v[182:185], v157 offset:50176
	ds_read_b128 v[186:189], v157 offset:51200
	ds_read_b128 v[190:193], v157 offset:52224
	ds_read_b128 v[194:197], v157 offset:53248
	ds_read_b128 v[198:201], v157 offset:54272
	ds_read_b128 v[202:205], v157 offset:55296
	ds_read_b128 v[206:209], v157 offset:56320
	global_load_lds_dwordx4 v[152:153], off
	s_add_i32 m0, s22, 0x2000
	s_add_u32 s20, s20, 0x40080
	v_lshl_add_u64 v[152:153], v[210:211], 0, s[2:3]
	s_addc_u32 s21, s21, 0
	s_add_i32 s22, s46, s24
	global_load_lds_dwordx4 v[152:153], off
	v_lshl_add_u64 v[152:153], s[20:21], 0, v[0:1]
	s_mov_b32 m0, s22
	s_nop 0
	global_load_lds_dwordx4 v[152:153], off
	v_lshl_add_u64 v[152:153], s[20:21], 0, v[130:131]
	s_add_i32 m0, s22, 0x2000
	s_nop 0
	global_load_lds_dwordx4 v[152:153], off
	v_lshl_add_u64 v[152:153], v[212:213], 0, s[2:3]
	s_mov_b32 m0, s33
	s_nop 0
	global_load_lds_dwordx4 v[152:153], off
	v_lshl_add_u64 v[152:153], v[214:215], 0, s[2:3]
	s_mov_b32 m0, s35
	s_nop 0
	global_load_lds_dwordx4 v[152:153], off
	s_waitcnt vmcnt(8)
	s_waitcnt lgkmcnt(0)
	s_setprio 1
	s_waitcnt lgkmcnt(0)
	s_barrier
	v_mfma_f32_16x16x32_bf16 v[62:65], v[140:143], v[178:181], v[62:65]
	v_mfma_f32_16x16x32_bf16 v[58:61], v[148:151], v[178:181], v[58:61]
	v_mfma_f32_16x16x32_bf16 v[46:49], v[140:143], v[186:189], v[46:49]
	v_mfma_f32_16x16x32_bf16 v[42:45], v[148:151], v[186:189], v[42:45]
	v_mfma_f32_16x16x32_bf16 v[30:33], v[140:143], v[194:197], v[30:33]
	v_mfma_f32_16x16x32_bf16 v[26:29], v[148:151], v[194:197], v[26:29]
	v_mfma_f32_16x16x32_bf16 v[14:17], v[140:143], v[202:205], v[14:17]
	v_mfma_f32_16x16x32_bf16 v[10:13], v[148:151], v[202:205], v[10:13]
	v_mfma_f32_16x16x32_bf16 v[62:65], v[144:147], v[182:185], v[62:65]
	v_mfma_f32_16x16x32_bf16 v[58:61], v[158:161], v[182:185], v[58:61]
	v_mfma_f32_16x16x32_bf16 v[46:49], v[144:147], v[190:193], v[46:49]
	v_mfma_f32_16x16x32_bf16 v[42:45], v[158:161], v[190:193], v[42:45]
	v_mfma_f32_16x16x32_bf16 v[30:33], v[144:147], v[198:201], v[30:33]
	v_mfma_f32_16x16x32_bf16 v[26:29], v[158:161], v[198:201], v[26:29]
	v_mfma_f32_16x16x32_bf16 v[14:17], v[144:147], v[206:209], v[14:17]
	v_mfma_f32_16x16x32_bf16 v[10:13], v[158:161], v[206:209], v[10:13]
	s_setprio 0
	s_setprio 1
	v_mfma_f32_16x16x32_bf16 v[54:57], v[162:165], v[178:181], v[54:57]
	v_mfma_f32_16x16x32_bf16 v[50:53], v[170:173], v[178:181], v[50:53]
	v_mfma_f32_16x16x32_bf16 v[38:41], v[162:165], v[186:189], v[38:41]
	v_mfma_f32_16x16x32_bf16 v[34:37], v[170:173], v[186:189], v[34:37]
	v_mfma_f32_16x16x32_bf16 v[22:25], v[162:165], v[194:197], v[22:25]
	v_mfma_f32_16x16x32_bf16 v[18:21], v[170:173], v[194:197], v[18:21]
	v_mfma_f32_16x16x32_bf16 v[6:9], v[162:165], v[202:205], v[6:9]
	v_mfma_f32_16x16x32_bf16 v[2:5], v[170:173], v[202:205], v[2:5]
	v_mfma_f32_16x16x32_bf16 v[54:57], v[166:169], v[182:185], v[54:57]
	v_mfma_f32_16x16x32_bf16 v[50:53], v[174:177], v[182:185], v[50:53]
	v_mfma_f32_16x16x32_bf16 v[38:41], v[166:169], v[190:193], v[38:41]
	v_mfma_f32_16x16x32_bf16 v[34:37], v[174:177], v[190:193], v[34:37]
	v_mfma_f32_16x16x32_bf16 v[22:25], v[166:169], v[198:201], v[22:25]
	v_mfma_f32_16x16x32_bf16 v[18:21], v[174:177], v[198:201], v[18:21]
	v_mfma_f32_16x16x32_bf16 v[6:9], v[166:169], v[206:209], v[6:9]
	v_mfma_f32_16x16x32_bf16 v[2:5], v[174:177], v[206:209], v[2:5]
	s_barrier
	s_setprio 0
	s_add_i32 s44, s44, 2
	s_add_u32 s18, s18, 0x100
	s_addc_u32 s19, s19, 0
	s_add_u32 s42, s42, 0x100
	s_addc_u32 s43, s43, 0
	s_cmp_gt_u32 s44, 13
	s_cbranch_scc0 .LBB0_156
	s_and_b64 vcc, exec, s[6:7]
	s_cbranch_vccz .LBB0_159
	s_barrier

; #define PG8_STAGE(bufoff, gbase, voff) do { _Pragma("unroll") for (int _i = 0; _i < 2; ++_i) \
;         __builtin_amdgcn_global_load_lds((const unsigned*)((const char*)(gbase) + (voff)[_i]), (PG8_LAS unsigned*)(lds + (bufoff) + ldsw + _i * 8192), 16, 0, 0); } while (0)
; #define PG8_LDA(dst, b, h) do { _Pragma("unroll") for (int m = 0; m < 4; ++m) _Pragma("unroll") for (int k = 0; k < 2; ++k) dst[m][k] = *(const PG8_LAS bf16x8*)(lds + PG8_SA(b, h) + aoff + m * 2048 + k * 1024); } while (0)
; #define PG8_LDB(dst, b, h) do { _Pragma("unroll") for (int n = 0; n < 2; ++n) _Pragma("unroll") for (int k = 0; k < 2; ++k) dst[n][k] = *(const PG8_LAS bf16x8*)(lds + PG8_SB(b, h) + boff + n * 2048 + k * 1024); } while (0)
; #define PG8_MMA(ai, bj, At, Bt) do { __builtin_amdgcn_s_setprio(1); _Pragma("unroll") for (int m = 0; m < 4; ++m) _Pragma("unroll") for (int n = 0; n < 2; ++n) _Pragma("unroll") for (int k = 0; k < 2; ++k) \
;         acc[ai][bj][m][n] = __builtin_amdgcn_mfma_f32_16x16x32_bf16(Bt[n][k], At[m][k], acc[ai][bj][m][n], 0, 0, 0); __builtin_amdgcn_s_setprio(0); } while (0)
; #define PG8_WAIT_V(n) asm volatile("s_waitcnt vmcnt(" #n ")" ::: "memory")
; #define PG8_WAIT_L(n) asm volatile("s_waitcnt lgkmcnt(" #n ")" ::: "memory")
; #define PG8_BAR __builtin_amdgcn_s_barrier()
; #define PG8_SCHED __builtin_amdgcn_sched_barrier(0)
; template <class Epi, class Sched, bool ALIGN_EPI = false, bool SP2 = false>
; __device__ __forceinline__ void gemm_phase(PG8_LAS unsigned char* lds, const Gemm g, const Sched& S, const Epi& E, const int wv) {
;     ...
;             const bool last = (t == nt - 2);
;             const char* a1 = cA + (size_t)(t + 1) * kstep;
;             const char* a2 = last ? nA : cA + (size_t)(t + 2) * kstep; const char* b2 = last ? nB : cB + (size_t)(t + 2) * kstep;
;             const char* a3 = a2 + kstep; const char* b3 = b2 + kstep;
;             if (last && has_next) S.a_ready(nxt);
;             if constexpr (SP2) {
;             PG8_LDB(B0, 0, 0); PG8_LDB(B1, 0, 1); PG8_SCHED; PG8_LDA(At, 0, 0); PG8_STAGE(PG8_SA(1, 1), a1 + hstep, voffA);
;             PG8_WAIT_V(8); PG8_WAIT_L(0); PG8_BAR; PG8_MMA(0, 0, At, B0); PG8_MMA(0, 1, At, B1); PG8_BAR; PG8_SCHED;
;             PG8_LDA(At, 0, 1); PG8_STAGE(PG8_SB(0, 0), b2, voffB); PG8_STAGE(PG8_SB(0, 1), b2 + hstep, voffB); PG8_STAGE(PG8_SA(0, 0), a2, voffA);
.LBB0_350:
	s_add_u32 s24, s22, 0xfffc0080
	s_addc_u32 s25, s23, -1
	s_add_i32 s48, 0, 0x10000
	s_cmp_eq_u32 s47, 12
	s_cselect_b32 s27, s13, s25
	s_cselect_b32 s26, s19, s24
	s_cselect_b32 s25, s11, s46
	s_cselect_b32 s24, s33, s45
	s_add_i32 s50, 0, 0x14000
	v_add_u32_e32 v126, s48, v183
	v_add_u32_e32 v168, s50, v183
	ds_read_b128 v[114:117], v126
	ds_read_b128 v[118:121], v126 offset:1024
	ds_read_b128 v[122:125], v126 offset:2048
	ds_read_b128 v[126:129], v126 offset:3072
	ds_read_b128 v[130:133], v168
	ds_read_b128 v[134:137], v168 offset:1024
	ds_read_b128 v[164:167], v168 offset:2048
	ds_read_b128 v[168:171], v168 offset:3072
	v_lshl_add_u64 v[180:181], s[22:23], 0, v[160:161]
	s_add_i32 m0, s21, 0xc000
	ds_read_b128 v[172:175], v185
	ds_read_b128 v[176:179], v185 offset:1024
	ds_read_b128 v[186:189], v185 offset:2048
	ds_read_b128 v[190:193], v185 offset:3072
	ds_read_b128 v[194:197], v185 offset:4096
	ds_read_b128 v[198:201], v185 offset:5120
	ds_read_b128 v[202:205], v185 offset:6144
	ds_read_b128 v[206:209], v185 offset:7168
	global_load_lds_dwordx4 v[180:181], off
	v_lshl_add_u64 v[180:181], s[22:23], 0, v[162:163]
	s_add_i32 m0, s21, 0xe000
	s_nop 0
	global_load_lds_dwordx4 v[180:181], off
	s_waitcnt vmcnt(8)
	s_waitcnt lgkmcnt(0)
	s_setprio 1
	s_waitcnt lgkmcnt(0)
	s_barrier
	v_mfma_f32_16x16x32_bf16 v[150:153], v[114:117], v[172:175], v[150:153]
	v_mfma_f32_16x16x32_bf16 v[146:149], v[122:125], v[172:175], v[146:149]
	v_mfma_f32_16x16x32_bf16 v[110:113], v[114:117], v[186:189], v[110:113]
	v_mfma_f32_16x16x32_bf16 v[106:109], v[122:125], v[186:189], v[106:109]
	v_mfma_f32_16x16x32_bf16 v[94:97], v[114:117], v[194:197], v[94:97]
	v_mfma_f32_16x16x32_bf16 v[90:93], v[122:125], v[194:197], v[90:93]
	v_mfma_f32_16x16x32_bf16 v[78:81], v[114:117], v[202:205], v[78:81]
	v_mfma_f32_16x16x32_bf16 v[74:77], v[122:125], v[202:205], v[74:77]
	v_mfma_f32_16x16x32_bf16 v[150:153], v[118:121], v[176:179], v[150:153]
	v_mfma_f32_16x16x32_bf16 v[146:149], v[126:129], v[176:179], v[146:149]
	v_mfma_f32_16x16x32_bf16 v[110:113], v[118:121], v[190:193], v[110:113]
	v_mfma_f32_16x16x32_bf16 v[106:109], v[126:129], v[190:193], v[106:109]
	v_mfma_f32_16x16x32_bf16 v[94:97], v[118:121], v[198:201], v[94:97]
	v_mfma_f32_16x16x32_bf16 v[90:93], v[126:129], v[198:201], v[90:93]
	v_mfma_f32_16x16x32_bf16 v[78:81], v[118:121], v[206:209], v[78:81]
	v_mfma_f32_16x16x32_bf16 v[74:77], v[126:129], v[206:209], v[74:77]
	s_setprio 0
	s_setprio 1
	v_mfma_f32_16x16x32_bf16 v[142:145], v[130:133], v[172:175], v[142:145]
	v_mfma_f32_16x16x32_bf16 v[138:141], v[164:167], v[172:175], v[138:141]
	v_mfma_f32_16x16x32_bf16 v[102:105], v[130:133], v[186:189], v[102:105]
	v_mfma_f32_16x16x32_bf16 v[98:101], v[164:167], v[186:189], v[98:101]
	v_mfma_f32_16x16x32_bf16 v[86:89], v[130:133], v[194:197], v[86:89]
	v_mfma_f32_16x16x32_bf16 v[82:85], v[164:167], v[194:197], v[82:85]
	v_mfma_f32_16x16x32_bf16 v[70:73], v[130:133], v[202:205], v[70:73]
	v_mfma_f32_16x16x32_bf16 v[66:69], v[164:167], v[202:205], v[66:69]
	v_mfma_f32_16x16x32_bf16 v[142:145], v[134:137], v[176:179], v[142:145]
	v_mfma_f32_16x16x32_bf16 v[138:141], v[168:171], v[176:179], v[138:141]
	v_mfma_f32_16x16x32_bf16 v[102:105], v[134:137], v[190:193], v[102:105]
	v_mfma_f32_16x16x32_bf16 v[98:101], v[168:171], v[190:193], v[98:101]
	v_mfma_f32_16x16x32_bf16 v[86:89], v[134:137], v[198:201], v[86:89]
	v_mfma_f32_16x16x32_bf16 v[82:85], v[168:171], v[198:201], v[82:85]
	v_mfma_f32_16x16x32_bf16 v[70:73], v[134:137], v[206:209], v[70:73]
	v_mfma_f32_16x16x32_bf16 v[66:69], v[168:171], v[206:209], v[66:69]
	s_barrier
	s_setprio 0
	s_add_i32 s48, s48, s36
	v_lshl_add_u64 v[180:181], s[24:25], 0, v[0:1]
	s_mov_b32 m0, s48
	ds_read_b128 v[172:175], v185 offset:16384
	ds_read_b128 v[176:179], v185 offset:17408
	ds_read_b128 v[186:189], v185 offset:18432
	ds_read_b128 v[190:193], v185 offset:19456
	ds_read_b128 v[194:197], v185 offset:20480
	ds_read_b128 v[198:201], v185 offset:21504
	ds_read_b128 v[202:205], v185 offset:22528
	ds_read_b128 v[206:209], v185 offset:23552
	global_load_lds_dwordx4 v[180:181], off
	s_add_i32 m0, s48, 0x2000
	s_add_u32 s48, s24, 0x40000
	v_lshl_add_u64 v[210:211], s[24:25], 0, v[158:159]
	s_addc_u32 s49, s25, 0
	s_add_i32 s50, s50, s36
	global_load_lds_dwordx4 v[210:211], off
	v_lshl_add_u64 v[212:213], s[48:49], 0, v[0:1]
	s_mov_b32 m0, s50
	v_lshl_add_u64 v[214:215], s[26:27], 0, v[156:157]
	global_load_lds_dwordx4 v[212:213], off
	v_lshl_add_u64 v[212:213], s[48:49], 0, v[158:159]
	s_add_i32 m0, s50, 0x2000
	s_nop 0
	global_load_lds_dwordx4 v[212:213], off
	v_lshl_add_u64 v[212:213], s[26:27], 0, v[154:155]
	s_mov_b32 m0, s21
	s_nop 0
	global_load_lds_dwordx4 v[212:213], off
	s_mov_b32 m0, s37
	s_nop 0
	global_load_lds_dwordx4 v[214:215], off
	s_waitcnt vmcnt(8)
	s_waitcnt lgkmcnt(0)
	s_setprio 1
	s_waitcnt lgkmcnt(0)
	s_barrier
; #define PG8_STAGE(bufoff, gbase, voff) do { _Pragma("unroll") for (int _i = 0; _i < 2; ++_i) \
;         __builtin_amdgcn_global_load_lds((const unsigned*)((const char*)(gbase) + (voff)[_i]), (PG8_LAS unsigned*)(lds + (bufoff) + ldsw + _i * 8192), 16, 0, 0); } while (0)
; #define PG8_LDA(dst, b, h) do { _Pragma("unroll") for (int m = 0; m < 4; ++m) _Pragma("unroll") for (int k = 0; k < 2; ++k) dst[m][k] = *(const PG8_LAS bf16x8*)(lds + PG8_SA(b, h) + aoff + m * 2048 + k * 1024); } while (0)
; #define PG8_LDB(dst, b, h) do { _Pragma("unroll") for (int n = 0; n < 2; ++n) _Pragma("unroll") for (int k = 0; k < 2; ++k) dst[n][k] = *(const PG8_LAS bf16x8*)(lds + PG8_SB(b, h) + boff + n * 2048 + k * 1024); } while (0)
; #define PG8_MMA(ai, bj, At, Bt) do { __builtin_amdgcn_s_setprio(1); _Pragma("unroll") for (int m = 0; m < 4; ++m) _Pragma("unroll") for (int n = 0; n < 2; ++n) _Pragma("unroll") for (int k = 0; k < 2; ++k) \
;         acc[ai][bj][m][n] = __builtin_amdgcn_mfma_f32_16x16x32_bf16(Bt[n][k], At[m][k], acc[ai][bj][m][n], 0, 0, 0); __builtin_amdgcn_s_setprio(0); } while (0)
; #define PG8_WAIT_V(n) asm volatile("s_waitcnt vmcnt(" #n ")" ::: "memory")
; #define PG8_WAIT_L(n) asm volatile("s_waitcnt lgkmcnt(" #n ")" ::: "memory")
; #define PG8_BAR __builtin_amdgcn_s_barrier()
; #define PG8_SCHED __builtin_amdgcn_sched_barrier(0)
; template <class Epi, class Sched, bool ALIGN_EPI = false, bool SP2 = false>
; __device__ __forceinline__ void gemm_phase(PG8_LAS unsigned char* lds, const Gemm g, const Sched& S, const Epi& E, const int wv) {
;     ...
;             PG8_WAIT_V(8); PG8_WAIT_L(0); PG8_BAR; PG8_MMA(1, 0, At, B0); PG8_MMA(1, 1, At, B1); PG8_BAR; PG8_SCHED;
;             PG8_LDB(B0, 1, 0); PG8_LDB(B1, 1, 1); PG8_SCHED; PG8_LDA(At, 1, 0); PG8_STAGE(PG8_SA(0, 1), a2 + hstep, voffA);
;             PG8_WAIT_V(8); PG8_WAIT_L(0); PG8_BAR; PG8_MMA(0, 0, At, B0); PG8_MMA(0, 1, At, B1); PG8_BAR; PG8_SCHED;
	v_mfma_f32_16x16x32_bf16 v[62:65], v[114:117], v[172:175], v[62:65]
	v_mfma_f32_16x16x32_bf16 v[58:61], v[122:125], v[172:175], v[58:61]
	v_mfma_f32_16x16x32_bf16 v[46:49], v[114:117], v[186:189], v[46:49]
	v_mfma_f32_16x16x32_bf16 v[42:45], v[122:125], v[186:189], v[42:45]
	v_mfma_f32_16x16x32_bf16 v[30:33], v[114:117], v[194:197], v[30:33]
	v_mfma_f32_16x16x32_bf16 v[26:29], v[122:125], v[194:197], v[26:29]
	v_mfma_f32_16x16x32_bf16 v[14:17], v[114:117], v[202:205], v[14:17]
	v_mfma_f32_16x16x32_bf16 v[10:13], v[122:125], v[202:205], v[10:13]
	v_mfma_f32_16x16x32_bf16 v[62:65], v[118:121], v[176:179], v[62:65]
	v_mfma_f32_16x16x32_bf16 v[58:61], v[126:129], v[176:179], v[58:61]
	v_mfma_f32_16x16x32_bf16 v[46:49], v[118:121], v[190:193], v[46:49]
	v_mfma_f32_16x16x32_bf16 v[42:45], v[126:129], v[190:193], v[42:45]
	v_mfma_f32_16x16x32_bf16 v[30:33], v[118:121], v[198:201], v[30:33]
	v_mfma_f32_16x16x32_bf16 v[26:29], v[126:129], v[198:201], v[26:29]
	v_mfma_f32_16x16x32_bf16 v[14:17], v[118:121], v[206:209], v[14:17]
	v_mfma_f32_16x16x32_bf16 v[10:13], v[126:129], v[206:209], v[10:13]
	s_setprio 0
	s_setprio 1
	v_mfma_f32_16x16x32_bf16 v[54:57], v[130:133], v[172:175], v[54:57]
	v_mfma_f32_16x16x32_bf16 v[50:53], v[164:167], v[172:175], v[50:53]
	v_mfma_f32_16x16x32_bf16 v[38:41], v[130:133], v[186:189], v[38:41]
	v_mfma_f32_16x16x32_bf16 v[34:37], v[164:167], v[186:189], v[34:37]
	v_mfma_f32_16x16x32_bf16 v[22:25], v[130:133], v[194:197], v[22:25]
	v_mfma_f32_16x16x32_bf16 v[18:21], v[164:167], v[194:197], v[18:21]
	v_mfma_f32_16x16x32_bf16 v[6:9], v[130:133], v[202:205], v[6:9]
	v_mfma_f32_16x16x32_bf16 v[2:5], v[164:167], v[202:205], v[2:5]
	v_mfma_f32_16x16x32_bf16 v[54:57], v[134:137], v[176:179], v[54:57]
	v_mfma_f32_16x16x32_bf16 v[50:53], v[168:171], v[176:179], v[50:53]
	v_mfma_f32_16x16x32_bf16 v[38:41], v[134:137], v[190:193], v[38:41]
	v_mfma_f32_16x16x32_bf16 v[34:37], v[168:171], v[190:193], v[34:37]
	v_mfma_f32_16x16x32_bf16 v[22:25], v[134:137], v[198:201], v[22:25]
	v_mfma_f32_16x16x32_bf16 v[18:21], v[168:171], v[198:201], v[18:21]
	v_mfma_f32_16x16x32_bf16 v[6:9], v[134:137], v[206:209], v[6:9]
	v_mfma_f32_16x16x32_bf16 v[2:5], v[168:171], v[206:209], v[2:5]
	s_barrier
	s_setprio 0
	s_add_i32 s48, 0, 0x18000
	s_add_i32 s49, 0, 0x1c000
	v_add_u32_e32 v126, s48, v183
	v_add_u32_e32 v168, s49, v183
	ds_read_b128 v[114:117], v126
	ds_read_b128 v[118:121], v126 offset:1024
	ds_read_b128 v[122:125], v126 offset:2048
	ds_read_b128 v[126:129], v126 offset:3072
	ds_read_b128 v[130:133], v168
	ds_read_b128 v[134:137], v168 offset:1024
	ds_read_b128 v[164:167], v168 offset:2048
	ds_read_b128 v[168:171], v168 offset:3072
	s_add_u32 s26, s26, 0x40000
	s_addc_u32 s27, s27, 0
	s_mov_b32 m0, s38
	v_lshl_add_u64 v[216:217], s[26:27], 0, v[154:155]
	ds_read_b128 v[172:175], v185 offset:32768
	ds_read_b128 v[176:179], v185 offset:33792
	ds_read_b128 v[186:189], v185 offset:34816
	ds_read_b128 v[190:193], v185 offset:35840
	ds_read_b128 v[194:197], v185 offset:36864
	ds_read_b128 v[198:201], v185 offset:37888
	ds_read_b128 v[202:205], v185 offset:38912
	ds_read_b128 v[206:209], v185 offset:39936
	global_load_lds_dwordx4 v[216:217], off
	v_lshl_add_u64 v[216:217], s[26:27], 0, v[156:157]
	s_mov_b32 m0, s39
	s_nop 0
	global_load_lds_dwordx4 v[216:217], off
	s_waitcnt vmcnt(8)
	s_waitcnt lgkmcnt(0)
	s_setprio 1
	s_waitcnt lgkmcnt(0)
	s_barrier
	v_mfma_f32_16x16x32_bf16 v[150:153], v[114:117], v[172:175], v[150:153]
	v_mfma_f32_16x16x32_bf16 v[146:149], v[122:125], v[172:175], v[146:149]
	v_mfma_f32_16x16x32_bf16 v[110:113], v[114:117], v[186:189], v[110:113]
	v_mfma_f32_16x16x32_bf16 v[106:109], v[122:125], v[186:189], v[106:109]
	v_mfma_f32_16x16x32_bf16 v[94:97], v[114:117], v[194:197], v[94:97]
	v_mfma_f32_16x16x32_bf16 v[90:93], v[122:125], v[194:197], v[90:93]
	v_mfma_f32_16x16x32_bf16 v[78:81], v[114:117], v[202:205], v[78:81]
	v_mfma_f32_16x16x32_bf16 v[74:77], v[122:125], v[202:205], v[74:77]
	v_mfma_f32_16x16x32_bf16 v[150:153], v[118:121], v[176:179], v[150:153]
	v_mfma_f32_16x16x32_bf16 v[146:149], v[126:129], v[176:179], v[146:149]
	v_mfma_f32_16x16x32_bf16 v[110:113], v[118:121], v[190:193], v[110:113]
	v_mfma_f32_16x16x32_bf16 v[106:109], v[126:129], v[190:193], v[106:109]
	v_mfma_f32_16x16x32_bf16 v[94:97], v[118:121], v[198:201], v[94:97]
	v_mfma_f32_16x16x32_bf16 v[90:93], v[126:129], v[198:201], v[90:93]
	v_mfma_f32_16x16x32_bf16 v[78:81], v[118:121], v[206:209], v[78:81]
	v_mfma_f32_16x16x32_bf16 v[74:77], v[126:129], v[206:209], v[74:77]
	s_setprio 0
	s_setprio 1
	v_mfma_f32_16x16x32_bf16 v[142:145], v[130:133], v[172:175], v[142:145]
	v_mfma_f32_16x16x32_bf16 v[138:141], v[164:167], v[172:175], v[138:141]
	v_mfma_f32_16x16x32_bf16 v[102:105], v[130:133], v[186:189], v[102:105]
	v_mfma_f32_16x16x32_bf16 v[98:101], v[164:167], v[186:189], v[98:101]
	v_mfma_f32_16x16x32_bf16 v[86:89], v[130:133], v[194:197], v[86:89]
	v_mfma_f32_16x16x32_bf16 v[82:85], v[164:167], v[194:197], v[82:85]
	v_mfma_f32_16x16x32_bf16 v[70:73], v[130:133], v[202:205], v[70:73]
	v_mfma_f32_16x16x32_bf16 v[66:69], v[164:167], v[202:205], v[66:69]
	v_mfma_f32_16x16x32_bf16 v[142:145], v[134:137], v[176:179], v[142:145]
	v_mfma_f32_16x16x32_bf16 v[138:141], v[168:171], v[176:179], v[138:141]
	v_mfma_f32_16x16x32_bf16 v[102:105], v[134:137], v[190:193], v[102:105]
	v_mfma_f32_16x16x32_bf16 v[98:101], v[168:171], v[190:193], v[98:101]
	v_mfma_f32_16x16x32_bf16 v[86:89], v[134:137], v[198:201], v[86:89]
	v_mfma_f32_16x16x32_bf16 v[82:85], v[168:171], v[198:201], v[82:85]
	v_mfma_f32_16x16x32_bf16 v[70:73], v[134:137], v[206:209], v[70:73]
	v_mfma_f32_16x16x32_bf16 v[66:69], v[168:171], v[206:209], v[66:69]
	s_barrier
; #define PG8_STAGE(bufoff, gbase, voff) do { _Pragma("unroll") for (int _i = 0; _i < 2; ++_i) \
;         __builtin_amdgcn_global_load_lds((const unsigned*)((const char*)(gbase) + (voff)[_i]), (PG8_LAS unsigned*)(lds + (bufoff) + ldsw + _i * 8192), 16, 0, 0); } while (0)
; #define PG8_LDA(dst, b, h) do { _Pragma("unroll") for (int m = 0; m < 4; ++m) _Pragma("unroll") for (int k = 0; k < 2; ++k) dst[m][k] = *(const PG8_LAS bf16x8*)(lds + PG8_SA(b, h) + aoff + m * 2048 + k * 1024); } while (0)
; #define PG8_MMA(ai, bj, At, Bt) do { __builtin_amdgcn_s_setprio(1); _Pragma("unroll") for (int m = 0; m < 4; ++m) _Pragma("unroll") for (int n = 0; n < 2; ++n) _Pragma("unroll") for (int k = 0; k < 2; ++k) \
;         acc[ai][bj][m][n] = __builtin_amdgcn_mfma_f32_16x16x32_bf16(Bt[n][k], At[m][k], acc[ai][bj][m][n], 0, 0, 0); __builtin_amdgcn_s_setprio(0); } while (0)
; #define PG8_WAIT_V(n) asm volatile("s_waitcnt vmcnt(" #n ")" ::: "memory")
; #define PG8_WAIT_L(n) asm volatile("s_waitcnt lgkmcnt(" #n ")" ::: "memory")
; #define PG8_BAR __builtin_amdgcn_s_barrier()
; #define PG8_SCHED __builtin_amdgcn_sched_barrier(0)
; template <class Epi, class Sched, bool ALIGN_EPI = false, bool SP2 = false>
; __device__ __forceinline__ void gemm_phase(PG8_LAS unsigned char* lds, const Gemm g, const Sched& S, const Epi& E, const int wv) {
;     ...
;             PG8_LDA(At, 1, 1); PG8_STAGE(PG8_SB(1, 0), b3, voffB); PG8_STAGE(PG8_SB(1, 1), b3 + hstep, voffB); PG8_STAGE(PG8_SA(1, 0), a3, voffA);
;             PG8_WAIT_V(8); PG8_WAIT_L(0); PG8_BAR; PG8_MMA(1, 0, At, B0); PG8_MMA(1, 1, At, B1); PG8_BAR; PG8_SCHED;
;     ...
;         if constexpr (ALIGN_EPI) { if (wr == 0) PG8_BAR; }
	s_setprio 0
	s_add_i32 s26, s48, s36
	v_lshl_add_u64 v[180:181], v[180:181], 0, s[2:3]
	s_mov_b32 m0, s26
	ds_read_b128 v[172:175], v185 offset:49152
	ds_read_b128 v[176:179], v185 offset:50176
	ds_read_b128 v[186:189], v185 offset:51200
	ds_read_b128 v[190:193], v185 offset:52224
	ds_read_b128 v[194:197], v185 offset:53248
	ds_read_b128 v[198:201], v185 offset:54272
	ds_read_b128 v[202:205], v185 offset:55296
	ds_read_b128 v[206:209], v185 offset:56320
	global_load_lds_dwordx4 v[180:181], off
	s_add_i32 m0, s26, 0x2000
	s_add_u32 s24, s24, 0x40080
	v_lshl_add_u64 v[180:181], v[210:211], 0, s[2:3]
	s_addc_u32 s25, s25, 0
	s_add_i32 s26, s49, s36
	global_load_lds_dwordx4 v[180:181], off
	v_lshl_add_u64 v[180:181], s[24:25], 0, v[0:1]
	s_mov_b32 m0, s26
	s_nop 0
	global_load_lds_dwordx4 v[180:181], off
	v_lshl_add_u64 v[180:181], s[24:25], 0, v[158:159]
	s_add_i32 m0, s26, 0x2000
	s_nop 0
	global_load_lds_dwordx4 v[180:181], off
	v_lshl_add_u64 v[180:181], v[212:213], 0, s[2:3]
	s_mov_b32 m0, s40
	s_nop 0
	global_load_lds_dwordx4 v[180:181], off
	v_lshl_add_u64 v[180:181], v[214:215], 0, s[2:3]
	s_mov_b32 m0, s41
	s_nop 0
	global_load_lds_dwordx4 v[180:181], off
	s_waitcnt vmcnt(8)
	s_waitcnt lgkmcnt(0)
	s_setprio 1
	s_waitcnt lgkmcnt(0)
	s_barrier
	v_mfma_f32_16x16x32_bf16 v[62:65], v[114:117], v[172:175], v[62:65]
	v_mfma_f32_16x16x32_bf16 v[58:61], v[122:125], v[172:175], v[58:61]
	v_mfma_f32_16x16x32_bf16 v[46:49], v[114:117], v[186:189], v[46:49]
	v_mfma_f32_16x16x32_bf16 v[42:45], v[122:125], v[186:189], v[42:45]
	v_mfma_f32_16x16x32_bf16 v[30:33], v[114:117], v[194:197], v[30:33]
	v_mfma_f32_16x16x32_bf16 v[26:29], v[122:125], v[194:197], v[26:29]
	v_mfma_f32_16x16x32_bf16 v[14:17], v[114:117], v[202:205], v[14:17]
	v_mfma_f32_16x16x32_bf16 v[10:13], v[122:125], v[202:205], v[10:13]
	v_mfma_f32_16x16x32_bf16 v[62:65], v[118:121], v[176:179], v[62:65]
	v_mfma_f32_16x16x32_bf16 v[58:61], v[126:129], v[176:179], v[58:61]
	v_mfma_f32_16x16x32_bf16 v[46:49], v[118:121], v[190:193], v[46:49]
	v_mfma_f32_16x16x32_bf16 v[42:45], v[126:129], v[190:193], v[42:45]
	v_mfma_f32_16x16x32_bf16 v[30:33], v[118:121], v[198:201], v[30:33]
	v_mfma_f32_16x16x32_bf16 v[26:29], v[126:129], v[198:201], v[26:29]
	v_mfma_f32_16x16x32_bf16 v[14:17], v[118:121], v[206:209], v[14:17]
	v_mfma_f32_16x16x32_bf16 v[10:13], v[126:129], v[206:209], v[10:13]
	s_setprio 0
	s_setprio 1
	v_mfma_f32_16x16x32_bf16 v[54:57], v[130:133], v[172:175], v[54:57]
	v_mfma_f32_16x16x32_bf16 v[50:53], v[164:167], v[172:175], v[50:53]
	v_mfma_f32_16x16x32_bf16 v[38:41], v[130:133], v[186:189], v[38:41]
	v_mfma_f32_16x16x32_bf16 v[34:37], v[164:167], v[186:189], v[34:37]
	v_mfma_f32_16x16x32_bf16 v[22:25], v[130:133], v[194:197], v[22:25]
	v_mfma_f32_16x16x32_bf16 v[18:21], v[164:167], v[194:197], v[18:21]
	v_mfma_f32_16x16x32_bf16 v[6:9], v[130:133], v[202:205], v[6:9]
	v_mfma_f32_16x16x32_bf16 v[2:5], v[164:167], v[202:205], v[2:5]
	v_mfma_f32_16x16x32_bf16 v[54:57], v[134:137], v[176:179], v[54:57]
	v_mfma_f32_16x16x32_bf16 v[50:53], v[168:171], v[176:179], v[50:53]
	v_mfma_f32_16x16x32_bf16 v[38:41], v[134:137], v[190:193], v[38:41]
	v_mfma_f32_16x16x32_bf16 v[34:37], v[168:171], v[190:193], v[34:37]
	v_mfma_f32_16x16x32_bf16 v[22:25], v[134:137], v[198:201], v[22:25]
	v_mfma_f32_16x16x32_bf16 v[18:21], v[168:171], v[198:201], v[18:21]
	v_mfma_f32_16x16x32_bf16 v[6:9], v[134:137], v[206:209], v[6:9]
	v_mfma_f32_16x16x32_bf16 v[2:5], v[168:171], v[206:209], v[2:5]
	s_barrier
	s_setprio 0
	s_add_i32 s47, s47, 2
	s_add_u32 s22, s22, 0x100
	s_addc_u32 s23, s23, 0
	s_add_u32 s45, s45, 0x100
	s_addc_u32 s46, s46, 0
	s_cmp_gt_u32 s47, 13
	s_cbranch_scc0 .LBB0_350
	s_and_b64 vcc, exec, s[8:9]
	s_cbranch_vccz .LBB0_353
	s_barrier

; #define PG8_STAGE(bufoff, gbase, voff) do { _Pragma("unroll") for (int _i = 0; _i < 2; ++_i) \
;         __builtin_amdgcn_global_load_lds((const unsigned*)((const char*)(gbase) + (voff)[_i]), (PG8_LAS unsigned*)(lds + (bufoff) + ldsw + _i * 8192), 16, 0, 0); } while (0)
; #define PG8_LDA(dst, b, h) do { _Pragma("unroll") for (int m = 0; m < 4; ++m) _Pragma("unroll") for (int k = 0; k < 2; ++k) dst[m][k] = *(const PG8_LAS bf16x8*)(lds + PG8_SA(b, h) + aoff + m * 2048 + k * 1024); } while (0)
; #define PG8_LDB(dst, b, h) do { _Pragma("unroll") for (int n = 0; n < 2; ++n) _Pragma("unroll") for (int k = 0; k < 2; ++k) dst[n][k] = *(const PG8_LAS bf16x8*)(lds + PG8_SB(b, h) + boff + n * 2048 + k * 1024); } while (0)
; #define PG8_MMA(ai, bj, At, Bt) do { __builtin_amdgcn_s_setprio(1); _Pragma("unroll") for (int m = 0; m < 4; ++m) _Pragma("unroll") for (int n = 0; n < 2; ++n) _Pragma("unroll") for (int k = 0; k < 2; ++k) \
;         acc[ai][bj][m][n] = __builtin_amdgcn_mfma_f32_16x16x32_bf16(Bt[n][k], At[m][k], acc[ai][bj][m][n], 0, 0, 0); __builtin_amdgcn_s_setprio(0); } while (0)
; #define PG8_WAIT_V(n) asm volatile("s_waitcnt vmcnt(" #n ")" ::: "memory")
; #define PG8_WAIT_L(n) asm volatile("s_waitcnt lgkmcnt(" #n ")" ::: "memory")
; #define PG8_BAR __builtin_amdgcn_s_barrier()
; #define PG8_SCHED __builtin_amdgcn_sched_barrier(0)
; template <class Epi, class Sched, bool ALIGN_EPI = false, bool SP2 = false>
; __device__ __forceinline__ void gemm_phase(PG8_LAS unsigned char* lds, const Gemm g, const Sched& S, const Epi& E, const int wv) {
;     ...
;             const bool last = (t == nt - 2);
;             const char* a1 = cA + (size_t)(t + 1) * kstep;
;             const char* a2 = last ? nA : cA + (size_t)(t + 2) * kstep; const char* b2 = last ? nB : cB + (size_t)(t + 2) * kstep;
;             const char* a3 = a2 + kstep; const char* b3 = b2 + kstep;
;             if (last && has_next) S.a_ready(nxt);
;             if constexpr (SP2) {
;             PG8_LDB(B0, 0, 0); PG8_LDB(B1, 0, 1); PG8_SCHED; PG8_LDA(At, 0, 0); PG8_STAGE(PG8_SA(1, 1), a1 + hstep, voffA);
;             PG8_WAIT_V(8); PG8_WAIT_L(0); PG8_BAR; PG8_MMA(0, 0, At, B0); PG8_MMA(0, 1, At, B1); PG8_BAR; PG8_SCHED;
;             PG8_LDA(At, 0, 1); PG8_STAGE(PG8_SB(0, 0), b2, voffB); PG8_STAGE(PG8_SB(0, 1), b2 + hstep, voffB); PG8_STAGE(PG8_SA(0, 0), a2, voffA);
.LBB0_428:
	s_add_u32 s20, s18, 0xfffc0080
	s_addc_u32 s21, s19, -1
	s_add_i32 s46, 0, 0x10000
	s_cmp_eq_u32 s45, 12
	s_cselect_b32 s23, s11, s21
	s_cselect_b32 s22, s33, s20
	s_cselect_b32 s21, s9, s44
	s_cselect_b32 s20, s42, s43
	s_add_i32 s48, 0, 0x14000
	v_add_u32_e32 v152, s46, v166
	v_add_u32_e32 v164, s48, v166
	ds_read_b128 v[140:143], v152
	ds_read_b128 v[144:147], v152 offset:1024
	ds_read_b128 v[148:151], v152 offset:2048
	ds_read_b128 v[152:155], v152 offset:3072
	ds_read_b128 v[156:159], v164
	ds_read_b128 v[160:163], v164 offset:1024
	ds_read_b128 v[170:173], v164 offset:2048
	ds_read_b128 v[174:177], v164 offset:3072
	v_lshl_add_u64 v[210:211], s[18:19], 0, v[136:137]
	s_add_i32 m0, s30, 0xc000
	ds_read_b128 v[178:181], v168
	ds_read_b128 v[182:185], v168 offset:1024
	ds_read_b128 v[186:189], v168 offset:2048
	ds_read_b128 v[190:193], v168 offset:3072
	ds_read_b128 v[194:197], v168 offset:4096
	ds_read_b128 v[198:201], v168 offset:5120
	ds_read_b128 v[202:205], v168 offset:6144
	ds_read_b128 v[206:209], v168 offset:7168
	global_load_lds_dwordx4 v[210:211], off
	v_lshl_add_u64 v[210:211], s[18:19], 0, v[138:139]
	s_add_i32 m0, s30, 0xe000
	s_nop 0
	global_load_lds_dwordx4 v[210:211], off
	s_waitcnt vmcnt(8)
	s_waitcnt lgkmcnt(0)
	s_setprio 1
	s_waitcnt lgkmcnt(0)
	s_barrier
	v_mfma_f32_16x16x32_bf16 v[126:129], v[140:143], v[178:181], v[126:129]
	v_mfma_f32_16x16x32_bf16 v[118:121], v[148:151], v[178:181], v[118:121]
	v_mfma_f32_16x16x32_bf16 v[110:113], v[140:143], v[186:189], v[110:113]
	v_mfma_f32_16x16x32_bf16 v[102:105], v[148:151], v[186:189], v[102:105]
	v_mfma_f32_16x16x32_bf16 v[94:97], v[140:143], v[194:197], v[94:97]
	v_mfma_f32_16x16x32_bf16 v[86:89], v[148:151], v[194:197], v[86:89]
	v_mfma_f32_16x16x32_bf16 v[78:81], v[140:143], v[202:205], v[78:81]
	v_mfma_f32_16x16x32_bf16 v[70:73], v[148:151], v[202:205], v[70:73]
	v_mfma_f32_16x16x32_bf16 v[126:129], v[144:147], v[182:185], v[126:129]
	v_mfma_f32_16x16x32_bf16 v[118:121], v[152:155], v[182:185], v[118:121]
	v_mfma_f32_16x16x32_bf16 v[110:113], v[144:147], v[190:193], v[110:113]
	v_mfma_f32_16x16x32_bf16 v[102:105], v[152:155], v[190:193], v[102:105]
	v_mfma_f32_16x16x32_bf16 v[94:97], v[144:147], v[198:201], v[94:97]
	v_mfma_f32_16x16x32_bf16 v[86:89], v[152:155], v[198:201], v[86:89]
	v_mfma_f32_16x16x32_bf16 v[78:81], v[144:147], v[206:209], v[78:81]
	v_mfma_f32_16x16x32_bf16 v[70:73], v[152:155], v[206:209], v[70:73]
	s_setprio 0
	s_setprio 1
	v_mfma_f32_16x16x32_bf16 v[122:125], v[156:159], v[178:181], v[122:125]
	v_mfma_f32_16x16x32_bf16 v[114:117], v[170:173], v[178:181], v[114:117]
	v_mfma_f32_16x16x32_bf16 v[106:109], v[156:159], v[186:189], v[106:109]
	v_mfma_f32_16x16x32_bf16 v[98:101], v[170:173], v[186:189], v[98:101]
	v_mfma_f32_16x16x32_bf16 v[90:93], v[156:159], v[194:197], v[90:93]
	v_mfma_f32_16x16x32_bf16 v[82:85], v[170:173], v[194:197], v[82:85]
	v_mfma_f32_16x16x32_bf16 v[74:77], v[156:159], v[202:205], v[74:77]
	v_mfma_f32_16x16x32_bf16 v[66:69], v[170:173], v[202:205], v[66:69]
	v_mfma_f32_16x16x32_bf16 v[122:125], v[160:163], v[182:185], v[122:125]
	v_mfma_f32_16x16x32_bf16 v[114:117], v[174:177], v[182:185], v[114:117]
	v_mfma_f32_16x16x32_bf16 v[106:109], v[160:163], v[190:193], v[106:109]
	v_mfma_f32_16x16x32_bf16 v[98:101], v[174:177], v[190:193], v[98:101]
	v_mfma_f32_16x16x32_bf16 v[90:93], v[160:163], v[198:201], v[90:93]
	v_mfma_f32_16x16x32_bf16 v[82:85], v[174:177], v[198:201], v[82:85]
	v_mfma_f32_16x16x32_bf16 v[74:77], v[160:163], v[206:209], v[74:77]
	v_mfma_f32_16x16x32_bf16 v[66:69], v[174:177], v[206:209], v[66:69]
	s_barrier
	s_setprio 0
	s_add_i32 s46, s46, s29
	v_lshl_add_u64 v[210:211], s[20:21], 0, v[0:1]
	s_mov_b32 m0, s46
	ds_read_b128 v[178:181], v168 offset:16384
	ds_read_b128 v[182:185], v168 offset:17408
	ds_read_b128 v[186:189], v168 offset:18432
	ds_read_b128 v[190:193], v168 offset:19456
	ds_read_b128 v[194:197], v168 offset:20480
	ds_read_b128 v[198:201], v168 offset:21504
	ds_read_b128 v[202:205], v168 offset:22528
	ds_read_b128 v[206:209], v168 offset:23552
	global_load_lds_dwordx4 v[210:211], off
	s_add_i32 m0, s46, 0x2000
	s_add_u32 s46, s20, 0x40000
	v_lshl_add_u64 v[212:213], s[20:21], 0, v[130:131]
	s_addc_u32 s47, s21, 0
	s_add_i32 s48, s48, s29
	global_load_lds_dwordx4 v[212:213], off
	v_lshl_add_u64 v[214:215], s[46:47], 0, v[0:1]
	s_mov_b32 m0, s48
	v_lshl_add_u64 v[216:217], s[22:23], 0, v[132:133]
	global_load_lds_dwordx4 v[214:215], off
	v_lshl_add_u64 v[214:215], s[46:47], 0, v[130:131]
	s_add_i32 m0, s48, 0x2000
	s_nop 0
	global_load_lds_dwordx4 v[214:215], off
	v_lshl_add_u64 v[214:215], s[22:23], 0, v[134:135]
	s_mov_b32 m0, s30
	s_nop 0
	global_load_lds_dwordx4 v[214:215], off
	s_mov_b32 m0, s31
	s_nop 0
	global_load_lds_dwordx4 v[216:217], off
	s_waitcnt vmcnt(8)
	s_waitcnt lgkmcnt(0)
	s_setprio 1
	s_waitcnt lgkmcnt(0)
	s_barrier
; #define PG8_STAGE(bufoff, gbase, voff) do { _Pragma("unroll") for (int _i = 0; _i < 2; ++_i) \
;         __builtin_amdgcn_global_load_lds((const unsigned*)((const char*)(gbase) + (voff)[_i]), (PG8_LAS unsigned*)(lds + (bufoff) + ldsw + _i * 8192), 16, 0, 0); } while (0)
; #define PG8_LDA(dst, b, h) do { _Pragma("unroll") for (int m = 0; m < 4; ++m) _Pragma("unroll") for (int k = 0; k < 2; ++k) dst[m][k] = *(const PG8_LAS bf16x8*)(lds + PG8_SA(b, h) + aoff + m * 2048 + k * 1024); } while (0)
; #define PG8_LDB(dst, b, h) do { _Pragma("unroll") for (int n = 0; n < 2; ++n) _Pragma("unroll") for (int k = 0; k < 2; ++k) dst[n][k] = *(const PG8_LAS bf16x8*)(lds + PG8_SB(b, h) + boff + n * 2048 + k * 1024); } while (0)
; #define PG8_MMA(ai, bj, At, Bt) do { __builtin_amdgcn_s_setprio(1); _Pragma("unroll") for (int m = 0; m < 4; ++m) _Pragma("unroll") for (int n = 0; n < 2; ++n) _Pragma("unroll") for (int k = 0; k < 2; ++k) \
;         acc[ai][bj][m][n] = __builtin_amdgcn_mfma_f32_16x16x32_bf16(Bt[n][k], At[m][k], acc[ai][bj][m][n], 0, 0, 0); __builtin_amdgcn_s_setprio(0); } while (0)
; #define PG8_WAIT_V(n) asm volatile("s_waitcnt vmcnt(" #n ")" ::: "memory")
; #define PG8_WAIT_L(n) asm volatile("s_waitcnt lgkmcnt(" #n ")" ::: "memory")
; #define PG8_BAR __builtin_amdgcn_s_barrier()
; #define PG8_SCHED __builtin_amdgcn_sched_barrier(0)
; template <class Epi, class Sched, bool ALIGN_EPI = false, bool SP2 = false>
; __device__ __forceinline__ void gemm_phase(PG8_LAS unsigned char* lds, const Gemm g, const Sched& S, const Epi& E, const int wv) {
;     ...
;             PG8_WAIT_V(8); PG8_WAIT_L(0); PG8_BAR; PG8_MMA(1, 0, At, B0); PG8_MMA(1, 1, At, B1); PG8_BAR; PG8_SCHED;
;             PG8_LDB(B0, 1, 0); PG8_LDB(B1, 1, 1); PG8_SCHED; PG8_LDA(At, 1, 0); PG8_STAGE(PG8_SA(0, 1), a2 + hstep, voffA);
;             PG8_WAIT_V(8); PG8_WAIT_L(0); PG8_BAR; PG8_MMA(0, 0, At, B0); PG8_MMA(0, 1, At, B1); PG8_BAR; PG8_SCHED;
	v_mfma_f32_16x16x32_bf16 v[62:65], v[140:143], v[178:181], v[62:65]
	v_mfma_f32_16x16x32_bf16 v[54:57], v[148:151], v[178:181], v[54:57]
	v_mfma_f32_16x16x32_bf16 v[46:49], v[140:143], v[186:189], v[46:49]
	v_mfma_f32_16x16x32_bf16 v[38:41], v[148:151], v[186:189], v[38:41]
	v_mfma_f32_16x16x32_bf16 v[30:33], v[140:143], v[194:197], v[30:33]
	v_mfma_f32_16x16x32_bf16 v[22:25], v[148:151], v[194:197], v[22:25]
	v_mfma_f32_16x16x32_bf16 v[14:17], v[140:143], v[202:205], v[14:17]
	v_mfma_f32_16x16x32_bf16 v[6:9], v[148:151], v[202:205], v[6:9]
	v_mfma_f32_16x16x32_bf16 v[62:65], v[144:147], v[182:185], v[62:65]
	v_mfma_f32_16x16x32_bf16 v[54:57], v[152:155], v[182:185], v[54:57]
	v_mfma_f32_16x16x32_bf16 v[46:49], v[144:147], v[190:193], v[46:49]
	v_mfma_f32_16x16x32_bf16 v[38:41], v[152:155], v[190:193], v[38:41]
	v_mfma_f32_16x16x32_bf16 v[30:33], v[144:147], v[198:201], v[30:33]
	v_mfma_f32_16x16x32_bf16 v[22:25], v[152:155], v[198:201], v[22:25]
	v_mfma_f32_16x16x32_bf16 v[14:17], v[144:147], v[206:209], v[14:17]
	v_mfma_f32_16x16x32_bf16 v[6:9], v[152:155], v[206:209], v[6:9]
	s_setprio 0
	s_setprio 1
	v_mfma_f32_16x16x32_bf16 v[58:61], v[156:159], v[178:181], v[58:61]
	v_mfma_f32_16x16x32_bf16 v[50:53], v[170:173], v[178:181], v[50:53]
	v_mfma_f32_16x16x32_bf16 v[42:45], v[156:159], v[186:189], v[42:45]
	v_mfma_f32_16x16x32_bf16 v[34:37], v[170:173], v[186:189], v[34:37]
	v_mfma_f32_16x16x32_bf16 v[26:29], v[156:159], v[194:197], v[26:29]
	v_mfma_f32_16x16x32_bf16 v[18:21], v[170:173], v[194:197], v[18:21]
	v_mfma_f32_16x16x32_bf16 v[10:13], v[156:159], v[202:205], v[10:13]
	v_mfma_f32_16x16x32_bf16 v[2:5], v[170:173], v[202:205], v[2:5]
	v_mfma_f32_16x16x32_bf16 v[58:61], v[160:163], v[182:185], v[58:61]
	v_mfma_f32_16x16x32_bf16 v[50:53], v[174:177], v[182:185], v[50:53]
	v_mfma_f32_16x16x32_bf16 v[42:45], v[160:163], v[190:193], v[42:45]
	v_mfma_f32_16x16x32_bf16 v[34:37], v[174:177], v[190:193], v[34:37]
	v_mfma_f32_16x16x32_bf16 v[26:29], v[160:163], v[198:201], v[26:29]
	v_mfma_f32_16x16x32_bf16 v[18:21], v[174:177], v[198:201], v[18:21]
	v_mfma_f32_16x16x32_bf16 v[10:13], v[160:163], v[206:209], v[10:13]
	v_mfma_f32_16x16x32_bf16 v[2:5], v[174:177], v[206:209], v[2:5]
	s_barrier
	s_setprio 0
	s_add_i32 s46, 0, 0x18000
	s_add_i32 s47, 0, 0x1c000
	v_add_u32_e32 v152, s46, v166
	v_add_u32_e32 v164, s47, v166
	ds_read_b128 v[140:143], v152
	ds_read_b128 v[144:147], v152 offset:1024
	ds_read_b128 v[148:151], v152 offset:2048
	ds_read_b128 v[152:155], v152 offset:3072
	ds_read_b128 v[156:159], v164
	ds_read_b128 v[160:163], v164 offset:1024
	ds_read_b128 v[170:173], v164 offset:2048
	ds_read_b128 v[174:177], v164 offset:3072
	s_add_u32 s22, s22, 0x40000
	s_addc_u32 s23, s23, 0
	s_mov_b32 m0, s36
	v_lshl_add_u64 v[218:219], s[22:23], 0, v[134:135]
	ds_read_b128 v[178:181], v168 offset:32768
	ds_read_b128 v[182:185], v168 offset:33792
	ds_read_b128 v[186:189], v168 offset:34816
	ds_read_b128 v[190:193], v168 offset:35840
	ds_read_b128 v[194:197], v168 offset:36864
	ds_read_b128 v[198:201], v168 offset:37888
	ds_read_b128 v[202:205], v168 offset:38912
	ds_read_b128 v[206:209], v168 offset:39936
	global_load_lds_dwordx4 v[218:219], off
	v_lshl_add_u64 v[218:219], s[22:23], 0, v[132:133]
	s_mov_b32 m0, s37
	s_nop 0
	global_load_lds_dwordx4 v[218:219], off
	s_waitcnt vmcnt(8)
	s_waitcnt lgkmcnt(0)
	s_setprio 1
	s_waitcnt lgkmcnt(0)
	s_barrier
	v_mfma_f32_16x16x32_bf16 v[126:129], v[140:143], v[178:181], v[126:129]
	v_mfma_f32_16x16x32_bf16 v[118:121], v[148:151], v[178:181], v[118:121]
	v_mfma_f32_16x16x32_bf16 v[110:113], v[140:143], v[186:189], v[110:113]
	v_mfma_f32_16x16x32_bf16 v[102:105], v[148:151], v[186:189], v[102:105]
	v_mfma_f32_16x16x32_bf16 v[94:97], v[140:143], v[194:197], v[94:97]
	v_mfma_f32_16x16x32_bf16 v[86:89], v[148:151], v[194:197], v[86:89]
	v_mfma_f32_16x16x32_bf16 v[78:81], v[140:143], v[202:205], v[78:81]
	v_mfma_f32_16x16x32_bf16 v[70:73], v[148:151], v[202:205], v[70:73]
	v_mfma_f32_16x16x32_bf16 v[126:129], v[144:147], v[182:185], v[126:129]
	v_mfma_f32_16x16x32_bf16 v[118:121], v[152:155], v[182:185], v[118:121]
	v_mfma_f32_16x16x32_bf16 v[110:113], v[144:147], v[190:193], v[110:113]
	v_mfma_f32_16x16x32_bf16 v[102:105], v[152:155], v[190:193], v[102:105]
	v_mfma_f32_16x16x32_bf16 v[94:97], v[144:147], v[198:201], v[94:97]
	v_mfma_f32_16x16x32_bf16 v[86:89], v[152:155], v[198:201], v[86:89]
	v_mfma_f32_16x16x32_bf16 v[78:81], v[144:147], v[206:209], v[78:81]
	v_mfma_f32_16x16x32_bf16 v[70:73], v[152:155], v[206:209], v[70:73]
	s_setprio 0
	s_setprio 1
	v_mfma_f32_16x16x32_bf16 v[122:125], v[156:159], v[178:181], v[122:125]
	v_mfma_f32_16x16x32_bf16 v[114:117], v[170:173], v[178:181], v[114:117]
	v_mfma_f32_16x16x32_bf16 v[106:109], v[156:159], v[186:189], v[106:109]
	v_mfma_f32_16x16x32_bf16 v[98:101], v[170:173], v[186:189], v[98:101]
	v_mfma_f32_16x16x32_bf16 v[90:93], v[156:159], v[194:197], v[90:93]
	v_mfma_f32_16x16x32_bf16 v[82:85], v[170:173], v[194:197], v[82:85]
	v_mfma_f32_16x16x32_bf16 v[74:77], v[156:159], v[202:205], v[74:77]
	v_mfma_f32_16x16x32_bf16 v[66:69], v[170:173], v[202:205], v[66:69]
	v_mfma_f32_16x16x32_bf16 v[122:125], v[160:163], v[182:185], v[122:125]
	v_mfma_f32_16x16x32_bf16 v[114:117], v[174:177], v[182:185], v[114:117]
	v_mfma_f32_16x16x32_bf16 v[106:109], v[160:163], v[190:193], v[106:109]
	v_mfma_f32_16x16x32_bf16 v[98:101], v[174:177], v[190:193], v[98:101]
	v_mfma_f32_16x16x32_bf16 v[90:93], v[160:163], v[198:201], v[90:93]
	v_mfma_f32_16x16x32_bf16 v[82:85], v[174:177], v[198:201], v[82:85]
	v_mfma_f32_16x16x32_bf16 v[74:77], v[160:163], v[206:209], v[74:77]
	v_mfma_f32_16x16x32_bf16 v[66:69], v[174:177], v[206:209], v[66:69]
	s_barrier
; #define PG8_STAGE(bufoff, gbase, voff) do { _Pragma("unroll") for (int _i = 0; _i < 2; ++_i) \
;         __builtin_amdgcn_global_load_lds((const unsigned*)((const char*)(gbase) + (voff)[_i]), (PG8_LAS unsigned*)(lds + (bufoff) + ldsw + _i * 8192), 16, 0, 0); } while (0)
; #define PG8_LDA(dst, b, h) do { _Pragma("unroll") for (int m = 0; m < 4; ++m) _Pragma("unroll") for (int k = 0; k < 2; ++k) dst[m][k] = *(const PG8_LAS bf16x8*)(lds + PG8_SA(b, h) + aoff + m * 2048 + k * 1024); } while (0)
; #define PG8_MMA(ai, bj, At, Bt) do { __builtin_amdgcn_s_setprio(1); _Pragma("unroll") for (int m = 0; m < 4; ++m) _Pragma("unroll") for (int n = 0; n < 2; ++n) _Pragma("unroll") for (int k = 0; k < 2; ++k) \
;         acc[ai][bj][m][n] = __builtin_amdgcn_mfma_f32_16x16x32_bf16(Bt[n][k], At[m][k], acc[ai][bj][m][n], 0, 0, 0); __builtin_amdgcn_s_setprio(0); } while (0)
; #define PG8_WAIT_V(n) asm volatile("s_waitcnt vmcnt(" #n ")" ::: "memory")
; #define PG8_WAIT_L(n) asm volatile("s_waitcnt lgkmcnt(" #n ")" ::: "memory")
; #define PG8_BAR __builtin_amdgcn_s_barrier()
; #define PG8_SCHED __builtin_amdgcn_sched_barrier(0)
; template <class Epi, class Sched, bool ALIGN_EPI = false, bool SP2 = false>
; __device__ __forceinline__ void gemm_phase(PG8_LAS unsigned char* lds, const Gemm g, const Sched& S, const Epi& E, const int wv) {
;     ...
;             PG8_LDA(At, 1, 1); PG8_STAGE(PG8_SB(1, 0), b3, voffB); PG8_STAGE(PG8_SB(1, 1), b3 + hstep, voffB); PG8_STAGE(PG8_SA(1, 0), a3, voffA);
;             PG8_WAIT_V(8); PG8_WAIT_L(0); PG8_BAR; PG8_MMA(1, 0, At, B0); PG8_MMA(1, 1, At, B1); PG8_BAR; PG8_SCHED;
	s_setprio 0
	s_add_i32 s22, s46, s29
	v_lshl_add_u64 v[210:211], v[210:211], 0, s[2:3]
	s_mov_b32 m0, s22
	ds_read_b128 v[178:181], v168 offset:49152
	ds_read_b128 v[182:185], v168 offset:50176
	ds_read_b128 v[186:189], v168 offset:51200
	ds_read_b128 v[190:193], v168 offset:52224
	ds_read_b128 v[194:197], v168 offset:53248
	ds_read_b128 v[198:201], v168 offset:54272
	ds_read_b128 v[202:205], v168 offset:55296
	ds_read_b128 v[206:209], v168 offset:56320
	global_load_lds_dwordx4 v[210:211], off
	s_add_i32 m0, s22, 0x2000
	s_add_u32 s20, s20, 0x40080
	v_lshl_add_u64 v[210:211], v[212:213], 0, s[2:3]
	s_addc_u32 s21, s21, 0
	s_add_i32 s22, s47, s29
	global_load_lds_dwordx4 v[210:211], off
	v_lshl_add_u64 v[210:211], s[20:21], 0, v[0:1]
	s_mov_b32 m0, s22
	s_nop 0
	global_load_lds_dwordx4 v[210:211], off
	v_lshl_add_u64 v[210:211], s[20:21], 0, v[130:131]
	s_add_i32 m0, s22, 0x2000
	s_nop 0
	global_load_lds_dwordx4 v[210:211], off
	v_lshl_add_u64 v[210:211], v[214:215], 0, s[2:3]
	s_mov_b32 m0, s39
	s_nop 0
	global_load_lds_dwordx4 v[210:211], off
	v_lshl_add_u64 v[210:211], v[216:217], 0, s[2:3]
	s_mov_b32 m0, s40
	s_nop 0
	global_load_lds_dwordx4 v[210:211], off
	s_waitcnt vmcnt(8)
	s_waitcnt lgkmcnt(0)
	s_setprio 1
	s_waitcnt lgkmcnt(0)
	s_barrier
	v_mfma_f32_16x16x32_bf16 v[62:65], v[140:143], v[178:181], v[62:65]
	v_mfma_f32_16x16x32_bf16 v[54:57], v[148:151], v[178:181], v[54:57]
	v_mfma_f32_16x16x32_bf16 v[46:49], v[140:143], v[186:189], v[46:49]
	v_mfma_f32_16x16x32_bf16 v[38:41], v[148:151], v[186:189], v[38:41]
	v_mfma_f32_16x16x32_bf16 v[30:33], v[140:143], v[194:197], v[30:33]
	v_mfma_f32_16x16x32_bf16 v[22:25], v[148:151], v[194:197], v[22:25]
	v_mfma_f32_16x16x32_bf16 v[14:17], v[140:143], v[202:205], v[14:17]
	v_mfma_f32_16x16x32_bf16 v[6:9], v[148:151], v[202:205], v[6:9]
	v_mfma_f32_16x16x32_bf16 v[62:65], v[144:147], v[182:185], v[62:65]
	v_mfma_f32_16x16x32_bf16 v[54:57], v[152:155], v[182:185], v[54:57]
	v_mfma_f32_16x16x32_bf16 v[46:49], v[144:147], v[190:193], v[46:49]
	v_mfma_f32_16x16x32_bf16 v[38:41], v[152:155], v[190:193], v[38:41]
	v_mfma_f32_16x16x32_bf16 v[30:33], v[144:147], v[198:201], v[30:33]
	v_mfma_f32_16x16x32_bf16 v[22:25], v[152:155], v[198:201], v[22:25]
	v_mfma_f32_16x16x32_bf16 v[14:17], v[144:147], v[206:209], v[14:17]
	v_mfma_f32_16x16x32_bf16 v[6:9], v[152:155], v[206:209], v[6:9]
	s_setprio 0
	s_setprio 1
	v_mfma_f32_16x16x32_bf16 v[58:61], v[156:159], v[178:181], v[58:61]
	v_mfma_f32_16x16x32_bf16 v[50:53], v[170:173], v[178:181], v[50:53]
	v_mfma_f32_16x16x32_bf16 v[42:45], v[156:159], v[186:189], v[42:45]
	v_mfma_f32_16x16x32_bf16 v[34:37], v[170:173], v[186:189], v[34:37]
	v_mfma_f32_16x16x32_bf16 v[26:29], v[156:159], v[194:197], v[26:29]
	v_mfma_f32_16x16x32_bf16 v[18:21], v[170:173], v[194:197], v[18:21]
	v_mfma_f32_16x16x32_bf16 v[10:13], v[156:159], v[202:205], v[10:13]
	v_mfma_f32_16x16x32_bf16 v[2:5], v[170:173], v[202:205], v[2:5]
	v_mfma_f32_16x16x32_bf16 v[58:61], v[160:163], v[182:185], v[58:61]
	v_mfma_f32_16x16x32_bf16 v[50:53], v[174:177], v[182:185], v[50:53]
	v_mfma_f32_16x16x32_bf16 v[42:45], v[160:163], v[190:193], v[42:45]
	v_mfma_f32_16x16x32_bf16 v[34:37], v[174:177], v[190:193], v[34:37]
	v_mfma_f32_16x16x32_bf16 v[26:29], v[160:163], v[198:201], v[26:29]
	v_mfma_f32_16x16x32_bf16 v[18:21], v[174:177], v[198:201], v[18:21]
	v_mfma_f32_16x16x32_bf16 v[10:13], v[160:163], v[206:209], v[10:13]
	v_mfma_f32_16x16x32_bf16 v[2:5], v[174:177], v[206:209], v[2:5]
	s_barrier
	s_setprio 0
	s_add_i32 s45, s45, 2
	s_add_u32 s18, s18, 0x100
	s_addc_u32 s19, s19, 0
	s_add_u32 s43, s43, 0x100
	s_addc_u32 s44, s44, 0
	s_cmp_gt_u32 s45, 13
	s_cbranch_scc0 .LBB0_428
	s_and_b64 vcc, exec, s[6:7]
	s_cbranch_vccz .LBB0_431
	s_barrier

; #define PG8_STAGE(bufoff, gbase, voff) do { _Pragma("unroll") for (int _i = 0; _i < 2; ++_i) \
;         __builtin_amdgcn_global_load_lds((const unsigned*)((const char*)(gbase) + (voff)[_i]), (PG8_LAS unsigned*)(lds + (bufoff) + ldsw + _i * 8192), 16, 0, 0); } while (0)
; #define PG8_LDA(dst, b, h) do { _Pragma("unroll") for (int m = 0; m < 4; ++m) _Pragma("unroll") for (int k = 0; k < 2; ++k) dst[m][k] = *(const PG8_LAS bf16x8*)(lds + PG8_SA(b, h) + aoff + m * 2048 + k * 1024); } while (0)
; #define PG8_LDB(dst, b, h) do { _Pragma("unroll") for (int n = 0; n < 2; ++n) _Pragma("unroll") for (int k = 0; k < 2; ++k) dst[n][k] = *(const PG8_LAS bf16x8*)(lds + PG8_SB(b, h) + boff + n * 2048 + k * 1024); } while (0)
; #define PG8_MMA(ai, bj, At, Bt) do { __builtin_amdgcn_s_setprio(1); _Pragma("unroll") for (int m = 0; m < 4; ++m) _Pragma("unroll") for (int n = 0; n < 2; ++n) _Pragma("unroll") for (int k = 0; k < 2; ++k) \
;         acc[ai][bj][m][n] = __builtin_amdgcn_mfma_f32_16x16x32_bf16(Bt[n][k], At[m][k], acc[ai][bj][m][n], 0, 0, 0); __builtin_amdgcn_s_setprio(0); } while (0)
; #define PG8_WAIT_V(n) asm volatile("s_waitcnt vmcnt(" #n ")" ::: "memory")
; #define PG8_WAIT_L(n) asm volatile("s_waitcnt lgkmcnt(" #n ")" ::: "memory")
; #define PG8_BAR __builtin_amdgcn_s_barrier()
; #define PG8_SCHED __builtin_amdgcn_sched_barrier(0)
; template <class Epi, class Sched, bool ALIGN_EPI = false, bool SP2 = false>
; __device__ __forceinline__ void gemm_phase(PG8_LAS unsigned char* lds, const Gemm g, const Sched& S, const Epi& E, const int wv) {
;     ...
;             const bool last = (t == nt - 2);
;             const char* a1 = cA + (size_t)(t + 1) * kstep;
;             const char* a2 = last ? nA : cA + (size_t)(t + 2) * kstep; const char* b2 = last ? nB : cB + (size_t)(t + 2) * kstep;
;             const char* a3 = a2 + kstep; const char* b3 = b2 + kstep;
;             if (last && has_next) S.a_ready(nxt);
;             if constexpr (SP2) {
;             PG8_LDB(B0, 0, 0); PG8_LDB(B1, 0, 1); PG8_SCHED; PG8_LDA(At, 0, 0); PG8_STAGE(PG8_SA(1, 1), a1 + hstep, voffA);
;             PG8_WAIT_V(8); PG8_WAIT_L(0); PG8_BAR; PG8_MMA(0, 0, At, B0); PG8_MMA(0, 1, At, B1); PG8_BAR; PG8_SCHED;
;             PG8_LDA(At, 0, 1); PG8_STAGE(PG8_SB(0, 0), b2, voffB); PG8_STAGE(PG8_SB(0, 1), b2 + hstep, voffB); PG8_STAGE(PG8_SA(0, 0), a2, voffA);
.LBB0_504:
	s_add_u32 s10, s8, 0x100
	s_addc_u32 s11, s9, 0
	s_add_i32 s52, 0, 0x10000
	s_cmp_eq_u32 s51, 40
	s_cselect_b32 s29, s1, s11
	s_cselect_b32 s28, s0, s10
	s_cselect_b32 s27, s25, s50
	s_cselect_b32 s26, s24, s49
	s_add_i32 s53, 0, 0x14000
	v_add_u32_e32 v142, s52, v187
	v_add_u32_e32 v168, s53, v187
	ds_read_b128 v[122:125], v142
	ds_read_b128 v[130:133], v142 offset:1024
	ds_read_b128 v[138:141], v142 offset:2048
	ds_read_b128 v[142:145], v142 offset:3072
	ds_read_b128 v[146:149], v168
	ds_read_b128 v[150:153], v168 offset:1024
	ds_read_b128 v[154:157], v168 offset:2048
	ds_read_b128 v[168:171], v168 offset:3072
	v_lshl_add_u64 v[184:185], s[8:9], 0, v[164:165]
	s_add_i32 m0, s37, 0xc000
	ds_read_b128 v[172:175], v189
	ds_read_b128 v[176:179], v189 offset:1024
	ds_read_b128 v[180:183], v189 offset:2048
	ds_read_b128 v[190:193], v189 offset:3072
	ds_read_b128 v[194:197], v189 offset:4096
	ds_read_b128 v[198:201], v189 offset:5120
	ds_read_b128 v[202:205], v189 offset:6144
	ds_read_b128 v[206:209], v189 offset:7168
	global_load_lds_dwordx4 v[184:185], off
	v_lshl_add_u64 v[184:185], s[8:9], 0, v[166:167]
	s_add_i32 m0, s37, 0xe000
	s_nop 0
	global_load_lds_dwordx4 v[184:185], off
	s_waitcnt vmcnt(8)
	s_waitcnt lgkmcnt(0)
	s_setprio 1
	s_waitcnt lgkmcnt(0)
	s_barrier
	v_mfma_f32_16x16x32_bf16 v[134:137], v[122:125], v[172:175], v[134:137]
	v_mfma_f32_16x16x32_bf16 v[126:129], v[138:141], v[172:175], v[126:129]
	v_mfma_f32_16x16x32_bf16 v[110:113], v[122:125], v[180:183], v[110:113]
	v_mfma_f32_16x16x32_bf16 v[106:109], v[138:141], v[180:183], v[106:109]
	v_mfma_f32_16x16x32_bf16 v[94:97], v[122:125], v[194:197], v[94:97]
	v_mfma_f32_16x16x32_bf16 v[90:93], v[138:141], v[194:197], v[90:93]
	v_mfma_f32_16x16x32_bf16 v[78:81], v[122:125], v[202:205], v[78:81]
	v_mfma_f32_16x16x32_bf16 v[74:77], v[138:141], v[202:205], v[74:77]
	v_mfma_f32_16x16x32_bf16 v[134:137], v[130:133], v[176:179], v[134:137]
	v_mfma_f32_16x16x32_bf16 v[126:129], v[142:145], v[176:179], v[126:129]
	v_mfma_f32_16x16x32_bf16 v[110:113], v[130:133], v[190:193], v[110:113]
	v_mfma_f32_16x16x32_bf16 v[106:109], v[142:145], v[190:193], v[106:109]
	v_mfma_f32_16x16x32_bf16 v[94:97], v[130:133], v[198:201], v[94:97]
	v_mfma_f32_16x16x32_bf16 v[90:93], v[142:145], v[198:201], v[90:93]
	v_mfma_f32_16x16x32_bf16 v[78:81], v[130:133], v[206:209], v[78:81]
	v_mfma_f32_16x16x32_bf16 v[74:77], v[142:145], v[206:209], v[74:77]
	s_setprio 0
	s_setprio 1
	v_mfma_f32_16x16x32_bf16 v[118:121], v[146:149], v[172:175], v[118:121]
	v_mfma_f32_16x16x32_bf16 v[114:117], v[154:157], v[172:175], v[114:117]
	v_mfma_f32_16x16x32_bf16 v[102:105], v[146:149], v[180:183], v[102:105]
	v_mfma_f32_16x16x32_bf16 v[98:101], v[154:157], v[180:183], v[98:101]
	v_mfma_f32_16x16x32_bf16 v[86:89], v[146:149], v[194:197], v[86:89]
	v_mfma_f32_16x16x32_bf16 v[82:85], v[154:157], v[194:197], v[82:85]
	v_mfma_f32_16x16x32_bf16 v[70:73], v[146:149], v[202:205], v[70:73]
	v_mfma_f32_16x16x32_bf16 v[66:69], v[154:157], v[202:205], v[66:69]
	v_mfma_f32_16x16x32_bf16 v[118:121], v[150:153], v[176:179], v[118:121]
	v_mfma_f32_16x16x32_bf16 v[114:117], v[168:171], v[176:179], v[114:117]
	v_mfma_f32_16x16x32_bf16 v[102:105], v[150:153], v[190:193], v[102:105]
	v_mfma_f32_16x16x32_bf16 v[98:101], v[168:171], v[190:193], v[98:101]
	v_mfma_f32_16x16x32_bf16 v[86:89], v[150:153], v[198:201], v[86:89]
	v_mfma_f32_16x16x32_bf16 v[82:85], v[168:171], v[198:201], v[82:85]
	v_mfma_f32_16x16x32_bf16 v[70:73], v[150:153], v[206:209], v[70:73]
	v_mfma_f32_16x16x32_bf16 v[66:69], v[168:171], v[206:209], v[66:69]
	s_barrier
	s_setprio 0
	s_add_i32 s8, s52, s36
	v_lshl_add_u64 v[184:185], s[26:27], 0, v[0:1]
	s_mov_b32 m0, s8
	ds_read_b128 v[172:175], v189 offset:16384
	ds_read_b128 v[176:179], v189 offset:17408
	ds_read_b128 v[180:183], v189 offset:18432
	ds_read_b128 v[190:193], v189 offset:19456
	ds_read_b128 v[194:197], v189 offset:20480
	ds_read_b128 v[198:201], v189 offset:21504
	ds_read_b128 v[202:205], v189 offset:22528
	ds_read_b128 v[206:209], v189 offset:23552
	global_load_lds_dwordx4 v[184:185], off
	s_add_i32 m0, s8, 0x2000
	s_add_u32 s8, s26, 0xb0000
	v_lshl_add_u64 v[210:211], s[26:27], 0, v[162:163]
	s_addc_u32 s9, s27, 0
	s_add_i32 s52, s53, s36
	global_load_lds_dwordx4 v[210:211], off
	v_lshl_add_u64 v[212:213], s[8:9], 0, v[0:1]
	s_mov_b32 m0, s52
	v_lshl_add_u64 v[214:215], s[28:29], 0, v[160:161]
	global_load_lds_dwordx4 v[212:213], off
	v_lshl_add_u64 v[212:213], s[8:9], 0, v[162:163]
	s_add_i32 m0, s52, 0x2000
	s_nop 0
	global_load_lds_dwordx4 v[212:213], off
	v_lshl_add_u64 v[212:213], s[28:29], 0, v[158:159]
	s_mov_b32 m0, s37
	s_nop 0
	global_load_lds_dwordx4 v[212:213], off
	s_mov_b32 m0, s38
	s_nop 0
	global_load_lds_dwordx4 v[214:215], off
	s_waitcnt vmcnt(8)
	s_waitcnt lgkmcnt(0)
	s_setprio 1
	s_waitcnt lgkmcnt(0)
	s_barrier
; #define PG8_STAGE(bufoff, gbase, voff) do { _Pragma("unroll") for (int _i = 0; _i < 2; ++_i) \
;         __builtin_amdgcn_global_load_lds((const unsigned*)((const char*)(gbase) + (voff)[_i]), (PG8_LAS unsigned*)(lds + (bufoff) + ldsw + _i * 8192), 16, 0, 0); } while (0)
; #define PG8_LDA(dst, b, h) do { _Pragma("unroll") for (int m = 0; m < 4; ++m) _Pragma("unroll") for (int k = 0; k < 2; ++k) dst[m][k] = *(const PG8_LAS bf16x8*)(lds + PG8_SA(b, h) + aoff + m * 2048 + k * 1024); } while (0)
; #define PG8_LDB(dst, b, h) do { _Pragma("unroll") for (int n = 0; n < 2; ++n) _Pragma("unroll") for (int k = 0; k < 2; ++k) dst[n][k] = *(const PG8_LAS bf16x8*)(lds + PG8_SB(b, h) + boff + n * 2048 + k * 1024); } while (0)
; #define PG8_MMA(ai, bj, At, Bt) do { __builtin_amdgcn_s_setprio(1); _Pragma("unroll") for (int m = 0; m < 4; ++m) _Pragma("unroll") for (int n = 0; n < 2; ++n) _Pragma("unroll") for (int k = 0; k < 2; ++k) \
;         acc[ai][bj][m][n] = __builtin_amdgcn_mfma_f32_16x16x32_bf16(Bt[n][k], At[m][k], acc[ai][bj][m][n], 0, 0, 0); __builtin_amdgcn_s_setprio(0); } while (0)
; #define PG8_WAIT_V(n) asm volatile("s_waitcnt vmcnt(" #n ")" ::: "memory")
; #define PG8_WAIT_L(n) asm volatile("s_waitcnt lgkmcnt(" #n ")" ::: "memory")
; #define PG8_BAR __builtin_amdgcn_s_barrier()
; #define PG8_SCHED __builtin_amdgcn_sched_barrier(0)
; template <class Epi, class Sched, bool ALIGN_EPI = false, bool SP2 = false>
; __device__ __forceinline__ void gemm_phase(PG8_LAS unsigned char* lds, const Gemm g, const Sched& S, const Epi& E, const int wv) {
;     ...
;             PG8_WAIT_V(8); PG8_WAIT_L(0); PG8_BAR; PG8_MMA(1, 0, At, B0); PG8_MMA(1, 1, At, B1); PG8_BAR; PG8_SCHED;
;             PG8_LDB(B0, 1, 0); PG8_LDB(B1, 1, 1); PG8_SCHED; PG8_LDA(At, 1, 0); PG8_STAGE(PG8_SA(0, 1), a2 + hstep, voffA);
;             PG8_WAIT_V(8); PG8_WAIT_L(0); PG8_BAR; PG8_MMA(0, 0, At, B0); PG8_MMA(0, 1, At, B1); PG8_BAR; PG8_SCHED;
	v_mfma_f32_16x16x32_bf16 v[62:65], v[122:125], v[172:175], v[62:65]
	v_mfma_f32_16x16x32_bf16 v[58:61], v[138:141], v[172:175], v[58:61]
	v_mfma_f32_16x16x32_bf16 v[46:49], v[122:125], v[180:183], v[46:49]
	v_mfma_f32_16x16x32_bf16 v[42:45], v[138:141], v[180:183], v[42:45]
	v_mfma_f32_16x16x32_bf16 v[30:33], v[122:125], v[194:197], v[30:33]
	v_mfma_f32_16x16x32_bf16 v[26:29], v[138:141], v[194:197], v[26:29]
	v_mfma_f32_16x16x32_bf16 v[14:17], v[122:125], v[202:205], v[14:17]
	v_mfma_f32_16x16x32_bf16 v[10:13], v[138:141], v[202:205], v[10:13]
	v_mfma_f32_16x16x32_bf16 v[62:65], v[130:133], v[176:179], v[62:65]
	v_mfma_f32_16x16x32_bf16 v[58:61], v[142:145], v[176:179], v[58:61]
	v_mfma_f32_16x16x32_bf16 v[46:49], v[130:133], v[190:193], v[46:49]
	v_mfma_f32_16x16x32_bf16 v[42:45], v[142:145], v[190:193], v[42:45]
	v_mfma_f32_16x16x32_bf16 v[30:33], v[130:133], v[198:201], v[30:33]
	v_mfma_f32_16x16x32_bf16 v[26:29], v[142:145], v[198:201], v[26:29]
	v_mfma_f32_16x16x32_bf16 v[14:17], v[130:133], v[206:209], v[14:17]
	v_mfma_f32_16x16x32_bf16 v[10:13], v[142:145], v[206:209], v[10:13]
	s_setprio 0
	s_setprio 1
	v_mfma_f32_16x16x32_bf16 v[54:57], v[146:149], v[172:175], v[54:57]
	v_mfma_f32_16x16x32_bf16 v[50:53], v[154:157], v[172:175], v[50:53]
	v_mfma_f32_16x16x32_bf16 v[38:41], v[146:149], v[180:183], v[38:41]
	v_mfma_f32_16x16x32_bf16 v[34:37], v[154:157], v[180:183], v[34:37]
	v_mfma_f32_16x16x32_bf16 v[22:25], v[146:149], v[194:197], v[22:25]
	v_mfma_f32_16x16x32_bf16 v[18:21], v[154:157], v[194:197], v[18:21]
	v_mfma_f32_16x16x32_bf16 v[6:9], v[146:149], v[202:205], v[6:9]
	v_mfma_f32_16x16x32_bf16 v[2:5], v[154:157], v[202:205], v[2:5]
	v_mfma_f32_16x16x32_bf16 v[54:57], v[150:153], v[176:179], v[54:57]
	v_mfma_f32_16x16x32_bf16 v[50:53], v[168:171], v[176:179], v[50:53]
	v_mfma_f32_16x16x32_bf16 v[38:41], v[150:153], v[190:193], v[38:41]
	v_mfma_f32_16x16x32_bf16 v[34:37], v[168:171], v[190:193], v[34:37]
	v_mfma_f32_16x16x32_bf16 v[22:25], v[150:153], v[198:201], v[22:25]
	v_mfma_f32_16x16x32_bf16 v[18:21], v[168:171], v[198:201], v[18:21]
	v_mfma_f32_16x16x32_bf16 v[6:9], v[150:153], v[206:209], v[6:9]
	v_mfma_f32_16x16x32_bf16 v[2:5], v[168:171], v[206:209], v[2:5]
	s_barrier
	s_setprio 0
	s_add_i32 s52, 0, 0x18000
	s_add_i32 s53, 0, 0x1c000
	v_add_u32_e32 v142, s52, v187
	v_add_u32_e32 v168, s53, v187
	ds_read_b128 v[122:125], v142
	ds_read_b128 v[130:133], v142 offset:1024
	ds_read_b128 v[138:141], v142 offset:2048
	ds_read_b128 v[142:145], v142 offset:3072
	ds_read_b128 v[146:149], v168
	ds_read_b128 v[150:153], v168 offset:1024
	ds_read_b128 v[154:157], v168 offset:2048
	ds_read_b128 v[168:171], v168 offset:3072
	s_add_u32 s8, s28, 0xb0000
	s_addc_u32 s9, s29, 0
	s_mov_b32 m0, s39
	v_lshl_add_u64 v[216:217], s[8:9], 0, v[158:159]
	ds_read_b128 v[172:175], v189 offset:32768
	ds_read_b128 v[176:179], v189 offset:33792
	ds_read_b128 v[180:183], v189 offset:34816
	ds_read_b128 v[190:193], v189 offset:35840
	ds_read_b128 v[194:197], v189 offset:36864
	ds_read_b128 v[198:201], v189 offset:37888
	ds_read_b128 v[202:205], v189 offset:38912
	ds_read_b128 v[206:209], v189 offset:39936
	global_load_lds_dwordx4 v[216:217], off
	v_lshl_add_u64 v[216:217], s[8:9], 0, v[160:161]
	s_mov_b32 m0, s40
	s_nop 0
	global_load_lds_dwordx4 v[216:217], off
	s_waitcnt vmcnt(8)
	s_waitcnt lgkmcnt(0)
	s_setprio 1
	s_waitcnt lgkmcnt(0)
	s_barrier
	v_mfma_f32_16x16x32_bf16 v[134:137], v[122:125], v[172:175], v[134:137]
	v_mfma_f32_16x16x32_bf16 v[126:129], v[138:141], v[172:175], v[126:129]
	v_mfma_f32_16x16x32_bf16 v[110:113], v[122:125], v[180:183], v[110:113]
	v_mfma_f32_16x16x32_bf16 v[106:109], v[138:141], v[180:183], v[106:109]
	v_mfma_f32_16x16x32_bf16 v[94:97], v[122:125], v[194:197], v[94:97]
	v_mfma_f32_16x16x32_bf16 v[90:93], v[138:141], v[194:197], v[90:93]
	v_mfma_f32_16x16x32_bf16 v[78:81], v[122:125], v[202:205], v[78:81]
	v_mfma_f32_16x16x32_bf16 v[74:77], v[138:141], v[202:205], v[74:77]
	v_mfma_f32_16x16x32_bf16 v[134:137], v[130:133], v[176:179], v[134:137]
	v_mfma_f32_16x16x32_bf16 v[126:129], v[142:145], v[176:179], v[126:129]
	v_mfma_f32_16x16x32_bf16 v[110:113], v[130:133], v[190:193], v[110:113]
	v_mfma_f32_16x16x32_bf16 v[106:109], v[142:145], v[190:193], v[106:109]
	v_mfma_f32_16x16x32_bf16 v[94:97], v[130:133], v[198:201], v[94:97]
	v_mfma_f32_16x16x32_bf16 v[90:93], v[142:145], v[198:201], v[90:93]
	v_mfma_f32_16x16x32_bf16 v[78:81], v[130:133], v[206:209], v[78:81]
	v_mfma_f32_16x16x32_bf16 v[74:77], v[142:145], v[206:209], v[74:77]
	s_setprio 0
	s_setprio 1
	v_mfma_f32_16x16x32_bf16 v[118:121], v[146:149], v[172:175], v[118:121]
	v_mfma_f32_16x16x32_bf16 v[114:117], v[154:157], v[172:175], v[114:117]
	v_mfma_f32_16x16x32_bf16 v[102:105], v[146:149], v[180:183], v[102:105]
	v_mfma_f32_16x16x32_bf16 v[98:101], v[154:157], v[180:183], v[98:101]
	v_mfma_f32_16x16x32_bf16 v[86:89], v[146:149], v[194:197], v[86:89]
	v_mfma_f32_16x16x32_bf16 v[82:85], v[154:157], v[194:197], v[82:85]
	v_mfma_f32_16x16x32_bf16 v[70:73], v[146:149], v[202:205], v[70:73]
	v_mfma_f32_16x16x32_bf16 v[66:69], v[154:157], v[202:205], v[66:69]
	v_mfma_f32_16x16x32_bf16 v[118:121], v[150:153], v[176:179], v[118:121]
	v_mfma_f32_16x16x32_bf16 v[114:117], v[168:171], v[176:179], v[114:117]
	v_mfma_f32_16x16x32_bf16 v[102:105], v[150:153], v[190:193], v[102:105]
	v_mfma_f32_16x16x32_bf16 v[98:101], v[168:171], v[190:193], v[98:101]
	v_mfma_f32_16x16x32_bf16 v[86:89], v[150:153], v[198:201], v[86:89]
	v_mfma_f32_16x16x32_bf16 v[82:85], v[168:171], v[198:201], v[82:85]
	v_mfma_f32_16x16x32_bf16 v[70:73], v[150:153], v[206:209], v[70:73]
	v_mfma_f32_16x16x32_bf16 v[66:69], v[168:171], v[206:209], v[66:69]
	s_barrier
; #define PG8_STAGE(bufoff, gbase, voff) do { _Pragma("unroll") for (int _i = 0; _i < 2; ++_i) \
;         __builtin_amdgcn_global_load_lds((const unsigned*)((const char*)(gbase) + (voff)[_i]), (PG8_LAS unsigned*)(lds + (bufoff) + ldsw + _i * 8192), 16, 0, 0); } while (0)
; #define PG8_LDA(dst, b, h) do { _Pragma("unroll") for (int m = 0; m < 4; ++m) _Pragma("unroll") for (int k = 0; k < 2; ++k) dst[m][k] = *(const PG8_LAS bf16x8*)(lds + PG8_SA(b, h) + aoff + m * 2048 + k * 1024); } while (0)
; #define PG8_MMA(ai, bj, At, Bt) do { __builtin_amdgcn_s_setprio(1); _Pragma("unroll") for (int m = 0; m < 4; ++m) _Pragma("unroll") for (int n = 0; n < 2; ++n) _Pragma("unroll") for (int k = 0; k < 2; ++k) \
;         acc[ai][bj][m][n] = __builtin_amdgcn_mfma_f32_16x16x32_bf16(Bt[n][k], At[m][k], acc[ai][bj][m][n], 0, 0, 0); __builtin_amdgcn_s_setprio(0); } while (0)
; #define PG8_WAIT_V(n) asm volatile("s_waitcnt vmcnt(" #n ")" ::: "memory")
; #define PG8_WAIT_L(n) asm volatile("s_waitcnt lgkmcnt(" #n ")" ::: "memory")
; #define PG8_BAR __builtin_amdgcn_s_barrier()
; #define PG8_SCHED __builtin_amdgcn_sched_barrier(0)
; template <class Epi, class Sched, bool ALIGN_EPI = false, bool SP2 = false>
; __device__ __forceinline__ void gemm_phase(PG8_LAS unsigned char* lds, const Gemm g, const Sched& S, const Epi& E, const int wv) {
;     ...
;             PG8_LDA(At, 1, 1); PG8_STAGE(PG8_SB(1, 0), b3, voffB); PG8_STAGE(PG8_SB(1, 1), b3 + hstep, voffB); PG8_STAGE(PG8_SA(1, 0), a3, voffA);
;             PG8_WAIT_V(8); PG8_WAIT_L(0); PG8_BAR; PG8_MMA(1, 0, At, B0); PG8_MMA(1, 1, At, B1); PG8_BAR; PG8_SCHED;
	s_setprio 0
	s_add_i32 s8, s52, s36
	v_lshl_add_u64 v[184:185], v[184:185], 0, s[2:3]
	s_mov_b32 m0, s8
	ds_read_b128 v[172:175], v189 offset:49152
	ds_read_b128 v[176:179], v189 offset:50176
	ds_read_b128 v[180:183], v189 offset:51200
	ds_read_b128 v[190:193], v189 offset:52224
	ds_read_b128 v[194:197], v189 offset:53248
	ds_read_b128 v[198:201], v189 offset:54272
	ds_read_b128 v[202:205], v189 offset:55296
	ds_read_b128 v[206:209], v189 offset:56320
	global_load_lds_dwordx4 v[184:185], off
	s_add_i32 m0, s8, 0x2000
	s_add_u32 s8, s26, 0xb0080
	v_lshl_add_u64 v[184:185], v[210:211], 0, s[2:3]
	s_addc_u32 s9, s27, 0
	s_add_i32 s26, s53, s36
	global_load_lds_dwordx4 v[184:185], off
	v_lshl_add_u64 v[184:185], s[8:9], 0, v[0:1]
	s_mov_b32 m0, s26
	s_nop 0
	global_load_lds_dwordx4 v[184:185], off
	v_lshl_add_u64 v[184:185], s[8:9], 0, v[162:163]
	s_add_i32 m0, s26, 0x2000
	s_nop 0
	global_load_lds_dwordx4 v[184:185], off
	v_lshl_add_u64 v[184:185], v[212:213], 0, s[2:3]
	s_mov_b32 m0, s42
	s_nop 0
	global_load_lds_dwordx4 v[184:185], off
	v_lshl_add_u64 v[184:185], v[214:215], 0, s[2:3]
	s_mov_b32 m0, s43
	s_nop 0
	global_load_lds_dwordx4 v[184:185], off
	s_waitcnt vmcnt(8)
	s_waitcnt lgkmcnt(0)
	s_setprio 1
	s_waitcnt lgkmcnt(0)
	s_barrier
	v_mfma_f32_16x16x32_bf16 v[62:65], v[122:125], v[172:175], v[62:65]
	v_mfma_f32_16x16x32_bf16 v[58:61], v[138:141], v[172:175], v[58:61]
	v_mfma_f32_16x16x32_bf16 v[46:49], v[122:125], v[180:183], v[46:49]
	v_mfma_f32_16x16x32_bf16 v[42:45], v[138:141], v[180:183], v[42:45]
	v_mfma_f32_16x16x32_bf16 v[30:33], v[122:125], v[194:197], v[30:33]
	v_mfma_f32_16x16x32_bf16 v[26:29], v[138:141], v[194:197], v[26:29]
	v_mfma_f32_16x16x32_bf16 v[14:17], v[122:125], v[202:205], v[14:17]
	v_mfma_f32_16x16x32_bf16 v[10:13], v[138:141], v[202:205], v[10:13]
	v_mfma_f32_16x16x32_bf16 v[62:65], v[130:133], v[176:179], v[62:65]
	v_mfma_f32_16x16x32_bf16 v[58:61], v[142:145], v[176:179], v[58:61]
	v_mfma_f32_16x16x32_bf16 v[46:49], v[130:133], v[190:193], v[46:49]
	v_mfma_f32_16x16x32_bf16 v[42:45], v[142:145], v[190:193], v[42:45]
	v_mfma_f32_16x16x32_bf16 v[30:33], v[130:133], v[198:201], v[30:33]
	v_mfma_f32_16x16x32_bf16 v[26:29], v[142:145], v[198:201], v[26:29]
	v_mfma_f32_16x16x32_bf16 v[14:17], v[130:133], v[206:209], v[14:17]
	v_mfma_f32_16x16x32_bf16 v[10:13], v[142:145], v[206:209], v[10:13]
	s_setprio 0
	s_setprio 1
	v_mfma_f32_16x16x32_bf16 v[54:57], v[146:149], v[172:175], v[54:57]
	v_mfma_f32_16x16x32_bf16 v[50:53], v[154:157], v[172:175], v[50:53]
	v_mfma_f32_16x16x32_bf16 v[38:41], v[146:149], v[180:183], v[38:41]
	v_mfma_f32_16x16x32_bf16 v[34:37], v[154:157], v[180:183], v[34:37]
	v_mfma_f32_16x16x32_bf16 v[22:25], v[146:149], v[194:197], v[22:25]
	v_mfma_f32_16x16x32_bf16 v[18:21], v[154:157], v[194:197], v[18:21]
	v_mfma_f32_16x16x32_bf16 v[6:9], v[146:149], v[202:205], v[6:9]
	v_mfma_f32_16x16x32_bf16 v[2:5], v[154:157], v[202:205], v[2:5]
	v_mfma_f32_16x16x32_bf16 v[54:57], v[150:153], v[176:179], v[54:57]
	v_mfma_f32_16x16x32_bf16 v[50:53], v[168:171], v[176:179], v[50:53]
	v_mfma_f32_16x16x32_bf16 v[38:41], v[150:153], v[190:193], v[38:41]
	v_mfma_f32_16x16x32_bf16 v[34:37], v[168:171], v[190:193], v[34:37]
	v_mfma_f32_16x16x32_bf16 v[22:25], v[150:153], v[198:201], v[22:25]
	v_mfma_f32_16x16x32_bf16 v[18:21], v[168:171], v[198:201], v[18:21]
	v_mfma_f32_16x16x32_bf16 v[6:9], v[150:153], v[206:209], v[6:9]
	v_mfma_f32_16x16x32_bf16 v[2:5], v[168:171], v[206:209], v[2:5]
	s_barrier
	s_setprio 0
	s_add_i32 s51, s51, 2
	s_add_u32 s49, s49, 0x100
	s_addc_u32 s50, s50, 0
	s_cmp_gt_u32 s51, 41
	s_mov_b64 s[8:9], s[10:11]
	s_cbranch_scc0 .LBB0_504
	s_and_b64 vcc, exec, s[18:19]
	s_cbranch_vccz .LBB0_507
	s_barrier
